# first half of every epilogue's stores write-through in in-proj, out-proj and FF2 (all units), so less dirty L2 data is left for the seam write-back
# baseline (speedup 1.0000x reference)
.Lmy_g1_afterload:
	s_and_b64 vcc, exec, s[36:37]
	s_waitcnt vmcnt(0)
	v_mov_b32_e32 v200, v181
	v_mov_b32_e32 v201, v182
	v_mov_b32_e32 v181, v183
	v_pk_add_f32 v[180:181], v[200:201], v[180:181]
	v_mov_b32_e32 v182, v185
	v_mov_b32_e32 v183, v186
	v_mov_b32_e32 v185, v187
	v_add_f32_e32 v159, v180, v181
	v_pk_add_f32 v[180:181], v[182:183], v[184:185]
	v_mov_b32_e32 v186, v189
	v_mov_b32_e32 v187, v190
	v_mov_b32_e32 v189, v191
	ds_bpermute_b32 v165, v161, v159
	v_add_f32_e32 v167, v180, v181
	v_pk_add_f32 v[182:183], v[186:187], v[188:189]
	ds_bpermute_b32 v173, v161, v167
	v_add_f32_e32 v169, v182, v183
	ds_bpermute_b32 v174, v161, v169
	s_waitcnt lgkmcnt(2)
	v_add_f32_e32 v159, v159, v165
	v_mov_b32_e32 v190, v193
	v_mov_b32_e32 v191, v194
	v_mov_b32_e32 v193, v195
	ds_bpermute_b32 v165, v163, v159
	s_waitcnt lgkmcnt(2)
	v_add_f32_e32 v167, v167, v173
	v_pk_add_f32 v[184:185], v[190:191], v[192:193]
	ds_bpermute_b32 v173, v163, v167
	v_add_f32_e32 v170, v184, v185
	s_waitcnt lgkmcnt(2)
	v_add_f32_e32 v169, v169, v174
	ds_bpermute_b32 v177, v161, v170
	ds_bpermute_b32 v174, v163, v169
	s_waitcnt lgkmcnt(3)
	v_add_f32_e32 v159, v159, v165
	v_fmamk_f32 v159, v159, 0x3a800000, v1
	s_waitcnt lgkmcnt(2)
	v_add_f32_e32 v165, v167, v173
	v_mov_b32_e32 v184, v205
	v_mov_b32_e32 v185, v206
	v_mov_b32_e32 v205, v207
	v_rsq_f32_e32 v180, v159
	v_fmamk_f32 v159, v165, 0x3a800000, v1
	v_pk_add_f32 v[184:185], v[184:185], v[204:205]
	v_rsq_f32_e32 v182, v159
	s_waitcnt lgkmcnt(0)
	v_add_f32_e32 v159, v169, v174
	v_add_f32_e32 v165, v170, v177
	v_add_f32_e32 v169, v184, v185
	ds_bpermute_b32 v167, v163, v165
	ds_bpermute_b32 v170, v161, v169
	v_fmamk_f32 v159, v159, 0x3a800000, v1
	v_rsq_f32_e32 v184, v159
	v_mov_b32_e32 v186, v209
	s_waitcnt lgkmcnt(1)
	v_add_f32_e32 v159, v165, v167
	s_waitcnt lgkmcnt(0)
	v_add_f32_e32 v165, v169, v170
	v_mov_b32_e32 v187, v210
	v_mov_b32_e32 v209, v211
	ds_bpermute_b32 v167, v163, v165
	v_pk_add_f32 v[186:187], v[186:187], v[208:209]
	v_mad_i64_i32 v[176:177], s[0:1], v176, s29, v[156:157]
	v_add_f32_e32 v169, v186, v187
	v_pk_fma_f32 v[130:131], v[130:131], v[180:181], v[146:147] op_sel_hi:[1,0,1]
	v_pk_fma_f32 v[128:129], v[128:129], v[180:181], v[144:145] op_sel_hi:[1,0,1]
	v_pk_fma_f32 v[192:193], v[126:127], v[180:181], v[142:143] op_sel_hi:[1,0,1]
	v_pk_fma_f32 v[126:127], v[124:125], v[180:181], v[140:141] op_sel_hi:[1,0,1]
	ds_bpermute_b32 v170, v161, v169
	v_cvt_pk_bf16_f32 v124, v128, v129
	v_cvt_pk_bf16_f32 v125, v130, v131
	v_cvt_pk_bf16_f32 v126, v126, v127
	v_cvt_pk_bf16_f32 v127, v192, v193
	v_lshl_add_u64 v[128:129], v[176:177], 1, s[24:25]
	s_nop 0
	global_store_dwordx4 v[128:129], v[124:127], off sc1
.Lmy_wt_g1_0r:
	v_pk_fma_f32 v[118:119], v[118:119], v[180:181], v[138:139] op_sel_hi:[1,0,1]
	v_pk_fma_f32 v[116:117], v[116:117], v[180:181], v[136:137] op_sel_hi:[1,0,1]
	v_pk_fma_f32 v[124:125], v[110:111], v[180:181], v[134:135] op_sel_hi:[1,0,1]
	v_pk_fma_f32 v[110:111], v[108:109], v[180:181], v[132:133] op_sel_hi:[1,0,1]
	v_fmamk_f32 v159, v159, 0x3a800000, v1
	v_cvt_pk_bf16_f32 v108, v116, v117
	v_cvt_pk_bf16_f32 v109, v118, v119
	v_cvt_pk_bf16_f32 v110, v110, v111
	v_cvt_pk_bf16_f32 v111, v124, v125
	v_rsq_f32_e32 v186, v159
	s_waitcnt lgkmcnt(1)
	v_add_f32_e32 v159, v165, v167
	v_mov_b32_e32 v190, v213
	v_mov_b32_e32 v191, v214
	v_mov_b32_e32 v213, v215
	s_nop 0
	global_store_dwordx4 v[128:129], v[108:111], off offset:256 sc1
.Lmy_wt_g1_1r:
	v_mad_i64_i32 v[116:117], s[0:1], v172, s29, v[156:157]
	s_nop 0
	v_pk_fma_f32 v[110:111], v[122:123], v[182:183], v[146:147] op_sel_hi:[1,0,1]
	v_pk_fma_f32 v[108:109], v[120:121], v[182:183], v[144:145] op_sel_hi:[1,0,1]
	v_pk_fma_f32 v[114:115], v[114:115], v[182:183], v[142:143] op_sel_hi:[1,0,1]
	v_pk_fma_f32 v[112:113], v[112:113], v[182:183], v[140:141] op_sel_hi:[1,0,1]
	v_fmamk_f32 v159, v159, 0x3a800000, v1
	v_pk_add_f32 v[190:191], v[190:191], v[212:213]
	v_cvt_pk_bf16_f32 v108, v108, v109
	v_cvt_pk_bf16_f32 v109, v110, v111
	v_cvt_pk_bf16_f32 v110, v112, v113
	v_cvt_pk_bf16_f32 v111, v114, v115
	v_lshl_add_u64 v[112:113], v[116:117], 1, s[24:25]
	v_rsq_f32_e32 v188, v159
	s_waitcnt lgkmcnt(0)
	v_add_f32_e32 v159, v169, v170
	v_add_f32_e32 v167, v190, v191
	s_nop 0
	global_store_dwordx4 v[112:113], v[108:111], off sc1
.Lmy_wt_g1_2r:
	v_pk_fma_f32 v[102:103], v[102:103], v[182:183], v[138:139] op_sel_hi:[1,0,1]
	v_pk_fma_f32 v[100:101], v[100:101], v[182:183], v[136:137] op_sel_hi:[1,0,1]
	v_pk_fma_f32 v[108:109], v[92:93], v[182:183], v[134:135] op_sel_hi:[1,0,1]
	v_pk_fma_f32 v[92:93], v[90:91], v[182:183], v[132:133] op_sel_hi:[1,0,1]
	ds_bpermute_b32 v165, v163, v159
	ds_bpermute_b32 v169, v161, v167
	v_cvt_pk_bf16_f32 v90, v100, v101
	v_cvt_pk_bf16_f32 v91, v102, v103
	v_cvt_pk_bf16_f32 v92, v92, v93
	v_cvt_pk_bf16_f32 v93, v108, v109
	v_mov_b32_e32 v190, v217
	v_mov_b32_e32 v191, v218
	v_mov_b32_e32 v217, v219
	s_nop 0
	global_store_dwordx4 v[112:113], v[90:93], off offset:256 sc1
.Lmy_wt_g1_3r:
	v_mad_i64_i32 v[100:101], s[0:1], v168, s29, v[156:157]
	s_nop 0
	v_pk_fma_f32 v[92:93], v[106:107], v[184:185], v[146:147] op_sel_hi:[1,0,1]
	v_pk_fma_f32 v[90:91], v[104:105], v[184:185], v[144:145] op_sel_hi:[1,0,1]
	v_pk_fma_f32 v[96:97], v[96:97], v[184:185], v[142:143] op_sel_hi:[1,0,1]
	v_pk_fma_f32 v[94:95], v[94:95], v[184:185], v[140:141] op_sel_hi:[1,0,1]
	v_pk_add_f32 v[190:191], v[190:191], v[216:217]
	v_cvt_pk_bf16_f32 v90, v90, v91
	v_cvt_pk_bf16_f32 v91, v92, v93
	v_cvt_pk_bf16_f32 v92, v94, v95
	v_cvt_pk_bf16_f32 v93, v96, v97
	v_lshl_add_u64 v[94:95], v[100:101], 1, s[24:25]
	v_add_f32_e32 v170, v190, v191
	s_nop 0
	global_store_dwordx4 v[94:95], v[90:93], off sc1
.Lmy_wt_g1_4r:
	v_pk_fma_f32 v[84:85], v[84:85], v[184:185], v[138:139] op_sel_hi:[1,0,1]
	v_pk_fma_f32 v[82:83], v[82:83], v[184:185], v[136:137] op_sel_hi:[1,0,1]
	v_pk_fma_f32 v[90:91], v[76:77], v[184:185], v[134:135] op_sel_hi:[1,0,1]
	v_pk_fma_f32 v[76:77], v[74:75], v[184:185], v[132:133] op_sel_hi:[1,0,1]
	ds_bpermute_b32 v161, v161, v170
	v_cvt_pk_bf16_f32 v74, v82, v83
	v_cvt_pk_bf16_f32 v75, v84, v85
	v_cvt_pk_bf16_f32 v76, v76, v77
	v_cvt_pk_bf16_f32 v77, v90, v91
	s_waitcnt lgkmcnt(2)
	v_add_f32_e32 v159, v159, v165
	s_waitcnt lgkmcnt(1)
	v_add_f32_e32 v165, v167, v169
	s_nop 0
	global_store_dwordx4 v[94:95], v[74:77], off offset:256 sc1
.Lmy_wt_g1_5r:
	v_mad_i64_i32 v[82:83], s[0:1], v166, s29, v[156:157]
	s_nop 0
	v_pk_fma_f32 v[76:77], v[88:89], v[186:187], v[146:147] op_sel_hi:[1,0,1]
	v_pk_fma_f32 v[74:75], v[86:87], v[186:187], v[144:145] op_sel_hi:[1,0,1]
	v_pk_fma_f32 v[80:81], v[80:81], v[186:187], v[142:143] op_sel_hi:[1,0,1]
	v_pk_fma_f32 v[78:79], v[78:79], v[186:187], v[140:141] op_sel_hi:[1,0,1]
	ds_bpermute_b32 v167, v163, v165
	v_cvt_pk_bf16_f32 v74, v74, v75
	v_cvt_pk_bf16_f32 v75, v76, v77
	v_cvt_pk_bf16_f32 v76, v78, v79
	v_cvt_pk_bf16_f32 v77, v80, v81
	v_lshl_add_u64 v[78:79], v[82:83], 1, s[24:25]
	s_nop 0
	global_store_dwordx4 v[78:79], v[74:77], off sc1
.Lmy_wt_g1_6r:
	v_pk_fma_f32 v[72:73], v[72:73], v[186:187], v[138:139] op_sel_hi:[1,0,1]
	v_pk_fma_f32 v[70:71], v[70:71], v[186:187], v[136:137] op_sel_hi:[1,0,1]
	v_pk_fma_f32 v[74:75], v[68:69], v[186:187], v[134:135] op_sel_hi:[1,0,1]
	v_pk_fma_f32 v[68:69], v[66:67], v[186:187], v[132:133] op_sel_hi:[1,0,1]
	v_fmamk_f32 v159, v159, 0x3a800000, v1
	v_cvt_pk_bf16_f32 v66, v70, v71
	v_cvt_pk_bf16_f32 v67, v72, v73
	v_cvt_pk_bf16_f32 v68, v68, v69
	v_cvt_pk_bf16_f32 v69, v74, v75
	s_waitcnt lgkmcnt(1)
	v_add_f32_e32 v161, v170, v161
	v_rsq_f32_e32 v190, v159
	s_nop 0
	global_store_dwordx4 v[78:79], v[66:69], off offset:256 sc1

.LBB0_867:
	s_lshl_b32 s6, s94, 8
	s_add_i32 s5, s6, 0xffffc000
	s_lshr_b32 s5, s5, 12
	s_ashr_i32 s4, s94, 5
	s_add_i32 s5, s5, 2
	s_cmp_lt_i32 s94, 64
	s_cselect_b32 s4, s4, s5
	s_ashr_i32 s5, s4, 31
	s_lshl_b64 s[4:5], s[4:5], 14
	v_lshl_or_b32 v164, s18, 8, v240
	s_add_u32 s44, s79, s4
	s_addc_u32 s45, s88, s5
	v_ashrrev_i32_e32 v165, 31, v164
	v_add_u32_e32 v222, s6, v238
	s_add_u32 s4, s89, s4
	v_lshlrev_b64 v[210:211], 1, v[164:165]
	v_ashrrev_i32_e32 v223, 31, v222
	v_lshlrev_b64 v[90:91], 2, v[164:165]
	s_addc_u32 s5, s90, s5
	v_lshl_add_u64 v[164:165], s[82:83], 0, v[210:211]
	v_lshlrev_b64 v[226:227], 11, v[222:223]
	v_lshl_add_u64 v[92:93], s[44:45], 0, v[90:91]
	v_lshl_add_u64 v[94:95], s[4:5], 0, v[90:91]
	v_lshl_add_u64 v[166:167], v[164:165], 0, v[226:227]
	global_load_dwordx4 v[120:123], v[92:93], off offset:16
	global_load_dwordx4 v[128:131], v[92:93], off
	global_load_dwordx4 v[108:111], v[94:95], off offset:16
	global_load_dwordx4 v[112:115], v[94:95], off
	global_load_dwordx4 v[100:103], v[92:93], off offset:528
	global_load_dwordx4 v[104:107], v[92:93], off offset:512
	s_nop 0
	global_load_dwordx4 v[90:93], v[94:95], off offset:528
	s_nop 0
	global_load_dwordx4 v[94:97], v[94:95], off offset:512
	s_nop 0
	global_load_dwordx4 v[192:195], v[166:167], off
	global_load_dwordx4 v[188:191], v[166:167], off offset:256
	v_or_b32_e32 v220, 16, v222
	v_ashrrev_i32_e32 v221, 31, v220
	v_or_b32_e32 v216, 32, v222
	v_or_b32_e32 v212, 48, v222
	v_lshlrev_b64 v[224:225], 11, v[220:221]
	v_ashrrev_i32_e32 v217, 31, v216
	v_ashrrev_i32_e32 v213, 31, v212
	v_lshl_add_u64 v[166:167], v[164:165], 0, v[224:225]
	v_lshlrev_b64 v[218:219], 11, v[216:217]
	v_lshlrev_b64 v[214:215], 11, v[212:213]
	global_load_dwordx4 v[184:187], v[166:167], off
	global_load_dwordx4 v[180:183], v[166:167], off offset:256
	v_lshl_add_u64 v[166:167], v[164:165], 0, v[218:219]
	v_lshl_add_u64 v[164:165], v[164:165], 0, v[214:215]
	global_load_dwordx4 v[176:179], v[166:167], off
	global_load_dwordx4 v[172:175], v[166:167], off offset:256
	global_load_dwordx4 v[168:171], v[164:165], off
	s_nop 0
	global_load_dwordx4 v[164:167], v[164:165], off offset:256
	v_and_b32_e32 v201, 64, v229
	v_xor_b32_e32 v200, 16, v229
	v_add_u32_e32 v201, 64, v201
	v_cmp_lt_i32_e32 vcc, v200, v201
	s_lshl_b32 s68, s18, 2
	s_ashr_i32 s69, s68, 31
	v_cndmask_b32_e32 v200, v229, v200, vcc
	v_lshlrev_b32_e32 v242, 2, v200
	v_xor_b32_e32 v200, 32, v229
	v_cmp_lt_i32_e32 vcc, v200, v201
	s_waitcnt vmcnt(0)
	v_and_b32_e32 v201, 0xffff0000, v192
	v_cndmask_b32_e32 v200, v229, v200, vcc
	s_andn2_b64 vcc, exec, s[40:41]
	v_lshlrev_b32_e32 v243, 2, v200
	v_lshlrev_b32_e32 v200, 16, v192
	v_lshlrev_b32_e32 v192, 16, v193
	v_and_b32_e32 v193, 0xffff0000, v193
	v_lshlrev_b32_e32 v202, 16, v194
	v_and_b32_e32 v203, 0xffff0000, v194
	v_lshlrev_b32_e32 v194, 16, v195
	v_and_b32_e32 v195, 0xffff0000, v195
	v_pk_fma_f32 v[162:163], v[162:163], v[130:131], v[192:193]
	v_pk_fma_f32 v[192:193], v[158:159], v[122:123], v[194:195]
	v_pk_fma_f32 v[194:195], v[156:157], v[120:121], v[202:203]
	v_pk_fma_f32 v[160:161], v[160:161], v[128:129], v[200:201]
	v_pk_mul_f32 v[156:157], v[194:195], v[194:195]
	v_pk_mul_f32 v[158:159], v[192:193], v[192:193]
	v_pk_fma_f32 v[156:157], v[160:161], v[160:161], v[156:157]
	v_pk_fma_f32 v[158:159], v[162:163], v[162:163], v[158:159]
	v_add_f32_e32 v156, v156, v157
	v_add_f32_e32 v157, v158, v159
	v_lshl_add_u64 v[200:201], s[82:83], 0, v[226:227]
	v_add_f32_e32 v202, v156, v157
	v_cvt_pk_bf16_f32 v156, v160, v161
	v_cvt_pk_bf16_f32 v157, v162, v163
	v_cvt_pk_bf16_f32 v158, v194, v195
	v_cvt_pk_bf16_f32 v159, v192, v193
	v_lshl_add_u64 v[200:201], v[200:201], 0, v[210:211]
	s_nop 0
	global_store_dwordx4 v[200:201], v[156:159], off sc1
.Lmy_wt_g2a_0r:
	s_nop 1
	v_pk_mul_f32 v[158:159], v[114:115], v[162:163]
	v_pk_mul_f32 v[156:157], v[112:113], v[160:161]
	v_pk_mul_f32 v[160:161], v[110:111], v[192:193]
	v_pk_mul_f32 v[162:163], v[108:109], v[194:195]
	v_cvt_pk_bf16_f32 v156, v156, v157
	v_cvt_pk_bf16_f32 v157, v158, v159
	v_cvt_pk_bf16_f32 v159, v160, v161
	v_lshl_add_u64 v[160:161], s[22:23], 0, v[226:227]
	v_cvt_pk_bf16_f32 v158, v162, v163
	v_lshl_add_u64 v[160:161], v[160:161], 0, v[210:211]
	s_nop 0
	global_store_dwordx4 v[160:161], v[156:159], off sc1
.Lmy_wt_g2a_1r:
	v_lshlrev_b32_e32 v162, 16, v190
	v_and_b32_e32 v163, 0xffff0000, v190
	v_lshlrev_b32_e32 v156, 16, v188
	v_and_b32_e32 v157, 0xffff0000, v188
	v_lshlrev_b32_e32 v158, 16, v189
	v_and_b32_e32 v159, 0xffff0000, v189
	v_lshlrev_b32_e32 v188, 16, v191
	v_and_b32_e32 v189, 0xffff0000, v191
	v_pk_fma_f32 v[152:153], v[152:153], v[104:105], v[156:157]
	v_pk_fma_f32 v[154:155], v[154:155], v[106:107], v[158:159]
	v_pk_fma_f32 v[156:157], v[150:151], v[102:103], v[188:189]
	v_pk_fma_f32 v[158:159], v[148:149], v[100:101], v[162:163]
	v_pk_mul_f32 v[150:151], v[156:157], v[156:157]
	v_pk_mul_f32 v[148:149], v[158:159], v[158:159]
	v_pk_fma_f32 v[150:151], v[154:155], v[154:155], v[150:151]
	v_pk_fma_f32 v[148:149], v[152:153], v[152:153], v[148:149]
	s_nop 0
	v_add_f32_e32 v148, v148, v149
	v_add_f32_e32 v149, v150, v151
	v_add_f32_e32 v148, v148, v149
	v_add_f32_e32 v162, v202, v148
	v_cvt_pk_bf16_f32 v148, v152, v153
	v_cvt_pk_bf16_f32 v149, v154, v155
	v_cvt_pk_bf16_f32 v150, v158, v159
	v_cvt_pk_bf16_f32 v151, v156, v157
	s_nop 0
	global_store_dwordx4 v[200:201], v[148:151], off offset:256 sc1
.Lmy_wt_g2a_2r:
	s_nop 1
	v_pk_mul_f32 v[150:151], v[96:97], v[154:155]
	v_pk_mul_f32 v[148:149], v[94:95], v[152:153]
	v_pk_mul_f32 v[152:153], v[92:93], v[156:157]
	v_pk_mul_f32 v[154:155], v[90:91], v[158:159]
	v_cvt_pk_bf16_f32 v148, v148, v149
	v_cvt_pk_bf16_f32 v149, v150, v151
	v_cvt_pk_bf16_f32 v150, v154, v155
	v_cvt_pk_bf16_f32 v151, v152, v153
	s_nop 0
	global_store_dwordx4 v[160:161], v[148:151], off offset:256 sc1

.LBB0_869:
	s_or_b64 exec, exec, s[70:71]
	v_add_u32_e32 v156, 0x80, v222
	v_ashrrev_i32_e32 v157, 31, v156
	v_lshlrev_b64 v[160:161], 11, v[156:157]
	s_waitcnt lgkmcnt(0)
	v_lshl_add_u64 v[148:149], s[82:83], 0, v[160:161]
	v_lshl_add_u64 v[158:159], v[148:149], 0, v[210:211]
	global_load_dwordx4 v[152:155], v[158:159], off
	global_load_dwordx4 v[148:151], v[158:159], off offset:256
	v_lshlrev_b32_e32 v162, 16, v184
	v_and_b32_e32 v163, 0xffff0000, v184
	v_lshlrev_b32_e32 v184, 16, v185
	v_and_b32_e32 v185, 0xffff0000, v185
	v_lshlrev_b32_e32 v188, 16, v186
	v_and_b32_e32 v189, 0xffff0000, v186
	v_lshlrev_b32_e32 v186, 16, v187
	v_and_b32_e32 v187, 0xffff0000, v187
	v_pk_fma_f32 v[144:145], v[144:145], v[128:129], v[162:163]
	v_pk_fma_f32 v[146:147], v[146:147], v[130:131], v[184:185]
	v_pk_fma_f32 v[162:163], v[142:143], v[122:123], v[186:187]
	v_pk_fma_f32 v[184:185], v[140:141], v[120:121], v[188:189]
	v_pk_mul_f32 v[142:143], v[162:163], v[162:163]
	v_pk_mul_f32 v[140:141], v[184:185], v[184:185]
	v_pk_fma_f32 v[142:143], v[146:147], v[146:147], v[142:143]
	v_pk_fma_f32 v[140:141], v[144:145], v[144:145], v[140:141]
	v_lshl_add_u64 v[186:187], s[82:83], 0, v[224:225]
	v_add_f32_e32 v140, v140, v141
	v_add_f32_e32 v141, v142, v143
	v_add_f32_e32 v188, v140, v141
	v_cvt_pk_bf16_f32 v140, v144, v145
	v_cvt_pk_bf16_f32 v141, v146, v147
	v_cvt_pk_bf16_f32 v142, v184, v185
	v_cvt_pk_bf16_f32 v143, v162, v163
	v_lshl_add_u64 v[186:187], v[186:187], 0, v[210:211]
	s_nop 0
	global_store_dwordx4 v[186:187], v[140:143], off sc1
.Lmy_wt_g2a_4r:
	s_nop 1
	v_pk_mul_f32 v[142:143], v[114:115], v[146:147]
	v_pk_mul_f32 v[140:141], v[112:113], v[144:145]
	v_pk_mul_f32 v[144:145], v[110:111], v[162:163]
	v_pk_mul_f32 v[146:147], v[108:109], v[184:185]
	v_cvt_pk_bf16_f32 v140, v140, v141
	v_cvt_pk_bf16_f32 v141, v142, v143
	v_cvt_pk_bf16_f32 v143, v144, v145
	v_lshl_add_u64 v[144:145], s[22:23], 0, v[224:225]
	v_cvt_pk_bf16_f32 v142, v146, v147
	v_lshl_add_u64 v[144:145], v[144:145], 0, v[210:211]
	s_nop 0
	global_store_dwordx4 v[144:145], v[140:143], off sc1
.Lmy_wt_g2a_5r:
	v_lshlrev_b32_e32 v146, 16, v182
	v_and_b32_e32 v147, 0xffff0000, v182
	v_lshlrev_b32_e32 v140, 16, v180
	v_and_b32_e32 v141, 0xffff0000, v180
	v_lshlrev_b32_e32 v142, 16, v181
	v_and_b32_e32 v143, 0xffff0000, v181
	v_lshlrev_b32_e32 v162, 16, v183
	v_and_b32_e32 v163, 0xffff0000, v183
	v_pk_fma_f32 v[136:137], v[136:137], v[104:105], v[140:141]
	v_pk_fma_f32 v[138:139], v[138:139], v[106:107], v[142:143]
	v_pk_fma_f32 v[140:141], v[134:135], v[102:103], v[162:163]
	v_pk_fma_f32 v[142:143], v[132:133], v[100:101], v[146:147]
	v_pk_mul_f32 v[134:135], v[140:141], v[140:141]
	v_pk_mul_f32 v[132:133], v[142:143], v[142:143]
	v_pk_fma_f32 v[134:135], v[138:139], v[138:139], v[134:135]
	v_pk_fma_f32 v[132:133], v[136:137], v[136:137], v[132:133]
	s_nop 0
	v_add_f32_e32 v132, v132, v133
	v_add_f32_e32 v133, v134, v135
	v_add_f32_e32 v132, v132, v133
	v_add_f32_e32 v146, v188, v132
	v_cvt_pk_bf16_f32 v132, v136, v137
	v_cvt_pk_bf16_f32 v133, v138, v139
	v_cvt_pk_bf16_f32 v134, v142, v143
	v_cvt_pk_bf16_f32 v135, v140, v141
	s_nop 0
	global_store_dwordx4 v[186:187], v[132:135], off offset:256 sc1
.Lmy_wt_g2a_6r:
	ds_bpermute_b32 v135, v242, v146
	v_pk_mul_f32 v[138:139], v[96:97], v[138:139]
	v_pk_mul_f32 v[132:133], v[94:95], v[136:137]
	v_pk_mul_f32 v[140:141], v[92:93], v[140:141]
	v_cvt_pk_bf16_f32 v134, v132, v133
	s_waitcnt lgkmcnt(0)
	v_add_f32_e32 v132, v146, v135
	ds_bpermute_b32 v133, v243, v132
	v_pk_mul_f32 v[136:137], v[90:91], v[142:143]
	v_cvt_pk_bf16_f32 v135, v138, v139
	v_cvt_pk_bf16_f32 v136, v136, v137
	v_cvt_pk_bf16_f32 v137, v140, v141
	s_nop 0
	global_store_dwordx4 v[144:145], v[134:137], off offset:256 sc1

.LBB0_871:
	s_or_b64 exec, exec, s[70:71]
	v_or_b32_e32 v140, 16, v156
	v_ashrrev_i32_e32 v141, 31, v140
	v_lshlrev_b64 v[144:145], 11, v[140:141]
	s_waitcnt lgkmcnt(0)
	v_lshl_add_u64 v[132:133], s[82:83], 0, v[144:145]
	v_lshl_add_u64 v[142:143], v[132:133], 0, v[210:211]
	global_load_dwordx4 v[136:139], v[142:143], off
	global_load_dwordx4 v[132:135], v[142:143], off offset:256
	v_lshlrev_b32_e32 v146, 16, v176
	v_and_b32_e32 v147, 0xffff0000, v176
	v_lshlrev_b32_e32 v162, 16, v177
	v_and_b32_e32 v163, 0xffff0000, v177
	v_lshlrev_b32_e32 v176, 16, v178
	v_and_b32_e32 v177, 0xffff0000, v178
	v_lshlrev_b32_e32 v178, 16, v179
	v_and_b32_e32 v179, 0xffff0000, v179
	v_pk_fma_f32 v[124:125], v[124:125], v[128:129], v[146:147]
	v_pk_fma_f32 v[126:127], v[126:127], v[130:131], v[162:163]
	v_pk_fma_f32 v[146:147], v[118:119], v[122:123], v[178:179]
	v_pk_fma_f32 v[162:163], v[116:117], v[120:121], v[176:177]
	v_pk_mul_f32 v[118:119], v[146:147], v[146:147]
	v_pk_mul_f32 v[116:117], v[162:163], v[162:163]
	v_pk_fma_f32 v[118:119], v[126:127], v[126:127], v[118:119]
	v_pk_fma_f32 v[116:117], v[124:125], v[124:125], v[116:117]
	v_lshl_add_u64 v[176:177], s[82:83], 0, v[218:219]
	v_add_f32_e32 v116, v116, v117
	v_add_f32_e32 v117, v118, v119
	v_add_f32_e32 v178, v116, v117
	v_cvt_pk_bf16_f32 v116, v124, v125
	v_cvt_pk_bf16_f32 v117, v126, v127
	v_cvt_pk_bf16_f32 v118, v162, v163
	v_cvt_pk_bf16_f32 v119, v146, v147
	v_lshl_add_u64 v[176:177], v[176:177], 0, v[210:211]
	s_nop 0
	global_store_dwordx4 v[176:177], v[116:119], off sc1
.Lmy_wt_g2a_8r:
	s_nop 1
	v_pk_mul_f32 v[118:119], v[114:115], v[126:127]
	v_pk_mul_f32 v[116:117], v[112:113], v[124:125]
	v_pk_mul_f32 v[124:125], v[110:111], v[146:147]
	v_pk_mul_f32 v[126:127], v[108:109], v[162:163]
	v_cvt_pk_bf16_f32 v116, v116, v117
	v_cvt_pk_bf16_f32 v117, v118, v119
	v_cvt_pk_bf16_f32 v119, v124, v125
	v_lshl_add_u64 v[124:125], s[22:23], 0, v[218:219]
	v_cvt_pk_bf16_f32 v118, v126, v127
	v_lshl_add_u64 v[124:125], v[124:125], 0, v[210:211]
	s_nop 0
	global_store_dwordx4 v[124:125], v[116:119], off sc1
.Lmy_wt_g2a_9r:
	v_lshlrev_b32_e32 v126, 16, v174
	v_and_b32_e32 v127, 0xffff0000, v174
	v_lshlrev_b32_e32 v116, 16, v172
	v_and_b32_e32 v117, 0xffff0000, v172
	v_lshlrev_b32_e32 v118, 16, v173
	v_and_b32_e32 v119, 0xffff0000, v173
	v_lshlrev_b32_e32 v146, 16, v175
	v_and_b32_e32 v147, 0xffff0000, v175
	v_pk_fma_f32 v[86:87], v[86:87], v[104:105], v[116:117]
	v_pk_fma_f32 v[88:89], v[88:89], v[106:107], v[118:119]
	v_pk_fma_f32 v[116:117], v[84:85], v[102:103], v[146:147]
	v_pk_fma_f32 v[118:119], v[82:83], v[100:101], v[126:127]
	v_pk_mul_f32 v[84:85], v[116:117], v[116:117]
	v_pk_mul_f32 v[82:83], v[118:119], v[118:119]
	v_pk_fma_f32 v[84:85], v[88:89], v[88:89], v[84:85]
	v_pk_fma_f32 v[82:83], v[86:87], v[86:87], v[82:83]
	s_nop 0
	v_add_f32_e32 v82, v82, v83
	v_add_f32_e32 v83, v84, v85
	v_add_f32_e32 v82, v82, v83
	v_add_f32_e32 v126, v178, v82
	v_cvt_pk_bf16_f32 v82, v86, v87
	v_cvt_pk_bf16_f32 v83, v88, v89
	v_cvt_pk_bf16_f32 v84, v118, v119
	v_cvt_pk_bf16_f32 v85, v116, v117
	s_nop 0
	global_store_dwordx4 v[176:177], v[82:85], off offset:256 sc1
.Lmy_wt_g2a_10r:
	ds_bpermute_b32 v85, v242, v126
	v_pk_mul_f32 v[88:89], v[96:97], v[88:89]
	v_pk_mul_f32 v[82:83], v[94:95], v[86:87]
	v_pk_mul_f32 v[116:117], v[92:93], v[116:117]
	v_cvt_pk_bf16_f32 v84, v82, v83
	s_waitcnt lgkmcnt(0)
	v_add_f32_e32 v82, v126, v85
	ds_bpermute_b32 v83, v243, v82
	v_pk_mul_f32 v[86:87], v[90:91], v[118:119]
	v_cvt_pk_bf16_f32 v85, v88, v89
	v_cvt_pk_bf16_f32 v86, v86, v87
	v_cvt_pk_bf16_f32 v87, v116, v117
	s_nop 0
	global_store_dwordx4 v[124:125], v[84:87], off offset:256 sc1

.LBB0_873:
	s_or_b64 exec, exec, s[70:71]
	v_or_b32_e32 v116, 32, v156
	v_ashrrev_i32_e32 v117, 31, v116
	v_lshlrev_b64 v[124:125], 11, v[116:117]
	s_waitcnt lgkmcnt(0)
	v_lshl_add_u64 v[82:83], s[82:83], 0, v[124:125]
	v_lshl_add_u64 v[118:119], v[82:83], 0, v[210:211]
	global_load_dwordx4 v[86:89], v[118:119], off
	global_load_dwordx4 v[82:85], v[118:119], off offset:256
	v_lshlrev_b32_e32 v126, 16, v168
	v_and_b32_e32 v127, 0xffff0000, v168
	v_lshlrev_b32_e32 v146, 16, v169
	v_and_b32_e32 v147, 0xffff0000, v169
	v_lshlrev_b32_e32 v162, 16, v170
	v_and_b32_e32 v163, 0xffff0000, v170
	v_lshlrev_b32_e32 v168, 16, v171
	v_and_b32_e32 v169, 0xffff0000, v171
	v_pk_fma_f32 v[78:79], v[78:79], v[128:129], v[126:127]
	v_pk_fma_f32 v[80:81], v[80:81], v[130:131], v[146:147]
	v_pk_fma_f32 v[126:127], v[76:77], v[122:123], v[168:169]
	v_pk_fma_f32 v[146:147], v[74:75], v[120:121], v[162:163]
	v_pk_mul_f32 v[76:77], v[126:127], v[126:127]
	v_pk_mul_f32 v[74:75], v[146:147], v[146:147]
	v_pk_fma_f32 v[76:77], v[80:81], v[80:81], v[76:77]
	v_pk_fma_f32 v[74:75], v[78:79], v[78:79], v[74:75]
	v_lshl_add_u64 v[162:163], s[82:83], 0, v[214:215]
	v_add_f32_e32 v74, v74, v75
	v_add_f32_e32 v75, v76, v77
	v_add_f32_e32 v168, v74, v75
	v_cvt_pk_bf16_f32 v74, v78, v79
	v_cvt_pk_bf16_f32 v75, v80, v81
	v_cvt_pk_bf16_f32 v76, v146, v147
	v_cvt_pk_bf16_f32 v77, v126, v127
	v_lshl_add_u64 v[162:163], v[162:163], 0, v[210:211]
	s_nop 0
	global_store_dwordx4 v[162:163], v[74:77], off sc1
.Lmy_wt_g2a_12r:
	s_nop 1
	v_pk_mul_f32 v[76:77], v[114:115], v[80:81]
	v_pk_mul_f32 v[74:75], v[112:113], v[78:79]
	v_pk_mul_f32 v[78:79], v[110:111], v[126:127]
	v_pk_mul_f32 v[80:81], v[108:109], v[146:147]
	v_cvt_pk_bf16_f32 v74, v74, v75
	v_cvt_pk_bf16_f32 v75, v76, v77
	v_cvt_pk_bf16_f32 v77, v78, v79
	v_lshl_add_u64 v[78:79], s[22:23], 0, v[214:215]
	v_cvt_pk_bf16_f32 v76, v80, v81
	v_lshl_add_u64 v[78:79], v[78:79], 0, v[210:211]
	s_nop 0
	global_store_dwordx4 v[78:79], v[74:77], off sc1
.Lmy_wt_g2a_13r:
	v_lshlrev_b32_e32 v80, 16, v166
	v_and_b32_e32 v81, 0xffff0000, v166
	v_lshlrev_b32_e32 v74, 16, v164
	v_and_b32_e32 v75, 0xffff0000, v164
	v_lshlrev_b32_e32 v76, 16, v165
	v_and_b32_e32 v77, 0xffff0000, v165
	v_lshlrev_b32_e32 v126, 16, v167
	v_and_b32_e32 v127, 0xffff0000, v167
	v_pk_fma_f32 v[70:71], v[70:71], v[104:105], v[74:75]
	v_pk_fma_f32 v[72:73], v[72:73], v[106:107], v[76:77]
	v_pk_fma_f32 v[74:75], v[68:69], v[102:103], v[126:127]
	v_pk_fma_f32 v[76:77], v[66:67], v[100:101], v[80:81]
	v_pk_mul_f32 v[68:69], v[74:75], v[74:75]
	v_pk_mul_f32 v[66:67], v[76:77], v[76:77]
	v_pk_fma_f32 v[68:69], v[72:73], v[72:73], v[68:69]
	v_pk_fma_f32 v[66:67], v[70:71], v[70:71], v[66:67]
	s_nop 0
	v_add_f32_e32 v66, v66, v67
	v_add_f32_e32 v67, v68, v69
	v_add_f32_e32 v66, v66, v67
	v_add_f32_e32 v80, v168, v66
	v_cvt_pk_bf16_f32 v66, v70, v71
	v_cvt_pk_bf16_f32 v67, v72, v73
	v_cvt_pk_bf16_f32 v68, v76, v77
	v_cvt_pk_bf16_f32 v69, v74, v75
	s_nop 0
	global_store_dwordx4 v[162:163], v[66:69], off offset:256 sc1
.Lmy_wt_g2a_14r:
	ds_bpermute_b32 v69, v242, v80
	v_pk_mul_f32 v[72:73], v[96:97], v[72:73]
	v_pk_mul_f32 v[66:67], v[94:95], v[70:71]
	v_pk_mul_f32 v[74:75], v[92:93], v[74:75]
	v_cvt_pk_bf16_f32 v68, v66, v67
	s_waitcnt lgkmcnt(0)
	v_add_f32_e32 v66, v80, v69
	ds_bpermute_b32 v67, v243, v66
	v_pk_mul_f32 v[70:71], v[90:91], v[76:77]
	v_cvt_pk_bf16_f32 v69, v72, v73
	v_cvt_pk_bf16_f32 v70, v70, v71
	v_cvt_pk_bf16_f32 v71, v74, v75
	s_nop 0
	global_store_dwordx4 v[78:79], v[68:71], off offset:256 sc1

.LBB0_911:
	s_lshl_b32 s15, s92, 8
	s_add_i32 s5, s15, 0xffffc000
	s_lshr_b32 s5, s5, 12
	s_ashr_i32 s4, s92, 5
	s_add_i32 s5, s5, 2
	s_cmp_lt_i32 s92, 64
	v_add_u32_e32 v214, s15, v222
	v_readlane_b32 s56, v252, 3
	s_cselect_b32 s4, s4, s5
	v_add_u32_e32 v88, 0xffffc000, v214
	v_ashrrev_i32_e32 v215, 31, v214
	v_cmp_gt_i32_e32 vcc, s21, v214
	v_readlane_b32 s57, v252, 4
	v_readlane_b32 s58, v252, 5
	v_readlane_b32 s59, v252, 6
	v_lshl_or_b32 v212, s18, 8, v224
	s_ashr_i32 s5, s4, 31
	v_cndmask_b32_e32 v89, 0, v215, vcc
	v_cndmask_b32_e32 v88, v88, v214, vcc
	v_mov_b32_e32 v170, s59
	v_mov_b32_e32 v171, s57
	v_mov_b32_e32 v172, s58
	v_mov_b32_e32 v173, s56
	s_lshl_b64 s[4:5], s[4:5], 14
	v_ashrrev_i32_e32 v213, 31, v212
	v_cndmask_b32_e32 v91, v170, v171, vcc
	v_cndmask_b32_e32 v90, v172, v173, vcc
	v_lshlrev_b64 v[88:89], 12, v[88:89]
	s_add_u32 s44, s79, s4
	v_lshlrev_b64 v[164:165], 2, v[212:213]
	v_lshl_add_u64 v[88:89], v[90:91], 0, v[88:89]
	s_addc_u32 s45, s88, s5
	v_lshl_add_u64 v[166:167], v[88:89], 0, v[164:165]
	v_lshl_add_u64 v[86:87], s[44:45], 0, v[164:165]
	global_load_dwordx4 v[238:241], v[166:167], off
	global_load_dwordx4 v[124:127], v[86:87], off
	global_load_dwordx4 v[116:119], v[86:87], off offset:16
	global_load_dwordx4 v[242:245], v[166:167], off offset:16
	s_add_u32 s4, s89, s4
	s_addc_u32 s5, s90, s5
	v_lshl_add_u64 v[90:91], s[4:5], 0, v[164:165]
	global_load_dwordx4 v[112:115], v[90:91], off
	global_load_dwordx4 v[108:111], v[90:91], off offset:16
	global_load_dwordx4 v[100:103], v[86:87], off offset:528
	global_load_dwordx4 v[104:107], v[86:87], off offset:512
	s_nop 0
	global_load_dwordx4 v[86:89], v[90:91], off offset:528
	s_nop 0
	global_load_dwordx4 v[90:93], v[90:91], off offset:512
	s_nop 0
	global_load_dwordx4 v[246:249], v[166:167], off offset:528
	global_load_dwordx4 v[200:203], v[166:167], off offset:512
	v_or_b32_e32 v220, 16, v214
	v_ashrrev_i32_e32 v221, 31, v220
	v_add_u32_e32 v166, 0xffffc010, v214
	v_cmp_gt_i32_e32 vcc, s21, v220
	v_or_b32_e32 v216, 32, v214
	v_ashrrev_i32_e32 v217, 31, v216
	v_cndmask_b32_e32 v167, 0, v221, vcc
	v_cndmask_b32_e32 v166, v166, v220, vcc
	v_cndmask_b32_e32 v169, v170, v171, vcc
	v_cndmask_b32_e32 v168, v172, v173, vcc
	v_lshlrev_b64 v[166:167], 12, v[166:167]
	v_lshl_add_u64 v[166:167], v[168:169], 0, v[166:167]
	v_lshl_add_u64 v[166:167], v[166:167], 0, v[164:165]
	global_load_dwordx4 v[188:191], v[166:167], off offset:16
	global_load_dwordx4 v[192:195], v[166:167], off
	global_load_dwordx4 v[180:183], v[166:167], off offset:528
	global_load_dwordx4 v[184:187], v[166:167], off offset:512
	v_add_u32_e32 v166, 0xffffc020, v214
	v_cmp_gt_i32_e32 vcc, s21, v216
	v_and_b32_e32 v211, 64, v229
	v_xor_b32_e32 v210, 16, v229
	v_cndmask_b32_e32 v167, 0, v217, vcc
	v_cndmask_b32_e32 v166, v166, v216, vcc
	v_cndmask_b32_e32 v169, v170, v171, vcc
	v_cndmask_b32_e32 v168, v172, v173, vcc
	v_lshlrev_b64 v[166:167], 12, v[166:167]
	v_lshl_add_u64 v[166:167], v[168:169], 0, v[166:167]
	v_lshl_add_u64 v[168:169], v[166:167], 0, v[164:165]
	global_load_dwordx4 v[172:175], v[168:169], off offset:16
	global_load_dwordx4 v[176:179], v[168:169], off
	global_load_dwordx4 v[164:167], v[168:169], off offset:528
	s_nop 0
	global_load_dwordx4 v[168:171], v[168:169], off offset:512
	v_add_u32_e32 v211, 64, v211
	v_xor_b32_e32 v218, 32, v229
	v_cmp_lt_i32_e32 vcc, v210, v211
	s_lshl_b32 s56, s18, 2
	v_readlane_b32 s68, v252, 15
	v_cndmask_b32_e32 v210, v229, v210, vcc
	v_cmp_lt_i32_e32 vcc, v218, v211
	v_lshlrev_b32_e32 v227, 2, v210
	v_readlane_b32 s69, v252, 16
	v_cndmask_b32_e32 v211, v229, v218, vcc
	v_lshlrev_b32_e32 v226, 2, v211
	v_lshlrev_b64 v[210:211], 1, v[212:213]
	s_ashr_i32 s57, s56, 31
	v_readlane_b32 s60, v252, 7
	v_readlane_b32 s61, v252, 8
	v_readlane_b32 s62, v252, 9
	v_readlane_b32 s63, v252, 10
	v_readlane_b32 s64, v252, 11
	v_readlane_b32 s65, v252, 12
	v_readlane_b32 s66, v252, 13
	v_readlane_b32 s67, v252, 14
	v_readlane_b32 s70, v252, 17
	v_readlane_b32 s71, v252, 18
	s_waitcnt vmcnt(0)
	v_pk_fma_f32 v[160:161], v[160:161], v[124:125], v[238:239]
	v_pk_fma_f32 v[162:163], v[162:163], v[126:127], v[240:241]
	v_pk_fma_f32 v[218:219], v[158:159], v[118:119], v[244:245]
	v_pk_fma_f32 v[238:239], v[156:157], v[116:117], v[242:243]
	v_pk_mul_f32 v[156:157], v[218:219], v[218:219]
	v_pk_mul_f32 v[158:159], v[238:239], v[238:239]
	v_pk_fma_f32 v[156:157], v[162:163], v[162:163], v[156:157]
	v_pk_fma_f32 v[158:159], v[160:161], v[160:161], v[158:159]
	v_lshlrev_b64 v[240:241], 11, v[214:215]
	v_add_f32_e32 v158, v158, v159
	v_add_f32_e32 v156, v156, v157
	v_lshl_add_u64 v[242:243], s[82:83], 0, v[240:241]
	v_add_f32_e32 v244, v158, v156
	v_cvt_pk_bf16_f32 v156, v160, v161
	v_cvt_pk_bf16_f32 v157, v162, v163
	v_cvt_pk_bf16_f32 v158, v238, v239
	v_cvt_pk_bf16_f32 v159, v218, v219
	v_lshl_add_u64 v[242:243], v[242:243], 0, v[210:211]
	s_andn2_b64 vcc, exec, s[38:39]
	s_nop 0
	global_store_dwordx4 v[242:243], v[156:159], off sc1
.Lmy_wt_g2b_0r:
	v_pk_fma_f32 v[154:155], v[154:155], v[106:107], v[202:203]
	v_pk_fma_f32 v[152:153], v[152:153], v[104:105], v[200:201]
	v_pk_mul_f32 v[158:159], v[114:115], v[162:163]
	v_pk_mul_f32 v[156:157], v[112:113], v[160:161]
	v_pk_mul_f32 v[160:161], v[110:111], v[218:219]
	v_pk_mul_f32 v[162:163], v[108:109], v[238:239]
	v_cvt_pk_bf16_f32 v156, v156, v157
	v_cvt_pk_bf16_f32 v157, v158, v159
	v_cvt_pk_bf16_f32 v159, v160, v161
	v_lshl_add_u64 v[160:161], s[22:23], 0, v[240:241]
	v_cvt_pk_bf16_f32 v158, v162, v163
	v_lshl_add_u64 v[160:161], v[160:161], 0, v[210:211]
	s_andn2_b64 vcc, exec, s[38:39]
	s_nop 0
	global_store_dwordx4 v[160:161], v[156:159], off sc1
.Lmy_wt_g2b_1r:
	s_nop 1
	v_pk_fma_f32 v[156:157], v[150:151], v[102:103], v[248:249]
	v_pk_fma_f32 v[158:159], v[148:149], v[100:101], v[246:247]
	v_pk_mul_f32 v[148:149], v[156:157], v[156:157]
	v_pk_mul_f32 v[150:151], v[158:159], v[158:159]
	v_pk_fma_f32 v[148:149], v[154:155], v[154:155], v[148:149]
	v_pk_fma_f32 v[150:151], v[152:153], v[152:153], v[150:151]
	v_add_f32_e32 v148, v148, v149
	v_add_f32_e32 v150, v150, v151
	v_add_f32_e32 v148, v150, v148
	v_add_f32_e32 v162, v244, v148
	v_cvt_pk_bf16_f32 v148, v152, v153
	v_cvt_pk_bf16_f32 v149, v154, v155
	v_cvt_pk_bf16_f32 v150, v158, v159
	v_cvt_pk_bf16_f32 v151, v156, v157
	s_andn2_b64 vcc, exec, s[38:39]
	s_nop 0
	global_store_dwordx4 v[242:243], v[148:151], off offset:256 sc1
.Lmy_wt_g2b_2r:
	ds_bpermute_b32 v151, v227, v162
	v_pk_mul_f32 v[154:155], v[92:93], v[154:155]
	v_pk_mul_f32 v[148:149], v[90:91], v[152:153]
	v_pk_mul_f32 v[156:157], v[88:89], v[156:157]
	v_cvt_pk_bf16_f32 v150, v148, v149
	s_waitcnt lgkmcnt(0)
	v_add_f32_e32 v148, v162, v151
	ds_bpermute_b32 v149, v226, v148
	v_pk_mul_f32 v[152:153], v[86:87], v[158:159]
	v_cvt_pk_bf16_f32 v151, v154, v155
	v_cvt_pk_bf16_f32 v152, v152, v153
	v_cvt_pk_bf16_f32 v153, v156, v157
	s_andn2_b64 vcc, exec, s[38:39]
	s_nop 0
	global_store_dwordx4 v[160:161], v[150:153], off offset:256 sc1

.LBB0_913:
	s_or_b64 exec, exec, s[68:69]
	v_readlane_b32 s4, v252, 3
	v_or_b32_e32 v218, 48, v214
	v_readlane_b32 s5, v252, 4
	v_readlane_b32 s7, v252, 6
	v_add_u32_e32 v148, 0xffffc030, v214
	v_ashrrev_i32_e32 v219, 31, v218
	v_cmp_gt_i32_e32 vcc, s21, v218
	v_readlane_b32 s6, v252, 5
	v_mov_b32_e32 v150, s7
	v_mov_b32_e32 v151, s5
	s_waitcnt lgkmcnt(0)
	v_cndmask_b32_e32 v149, 0, v219, vcc
	v_cndmask_b32_e32 v148, v148, v218, vcc
	v_cndmask_b32_e32 v151, v150, v151, vcc
	v_mov_b32_e32 v150, s6
	v_mov_b32_e32 v152, s4
	v_cndmask_b32_e32 v150, v150, v152, vcc
	v_lshlrev_b64 v[148:149], 12, v[148:149]
	v_lshl_add_u64 v[148:149], v[150:151], 0, v[148:149]
	v_lshl_add_u64 v[152:153], v[212:213], 2, v[148:149]
	global_load_dwordx4 v[156:159], v[152:153], off offset:16
	global_load_dwordx4 v[160:163], v[152:153], off
	global_load_dwordx4 v[148:151], v[152:153], off offset:528
	s_nop 0
	global_load_dwordx4 v[152:155], v[152:153], off offset:512
	v_pk_fma_f32 v[190:191], v[142:143], v[118:119], v[190:191]
	v_pk_fma_f32 v[188:189], v[140:141], v[116:117], v[188:189]
	v_pk_fma_f32 v[146:147], v[146:147], v[126:127], v[194:195]
	v_pk_fma_f32 v[144:145], v[144:145], v[124:125], v[192:193]
	v_pk_mul_f32 v[140:141], v[190:191], v[190:191]
	v_pk_mul_f32 v[142:143], v[188:189], v[188:189]
	v_pk_fma_f32 v[140:141], v[146:147], v[146:147], v[140:141]
	v_pk_fma_f32 v[142:143], v[144:145], v[144:145], v[142:143]
	v_lshlrev_b64 v[192:193], 11, v[220:221]
	v_add_f32_e32 v142, v142, v143
	v_add_f32_e32 v140, v140, v141
	v_lshl_add_u64 v[194:195], s[82:83], 0, v[192:193]
	v_add_f32_e32 v200, v142, v140
	v_cvt_pk_bf16_f32 v140, v144, v145
	v_cvt_pk_bf16_f32 v141, v146, v147
	v_cvt_pk_bf16_f32 v142, v188, v189
	v_cvt_pk_bf16_f32 v143, v190, v191
	v_lshl_add_u64 v[194:195], v[194:195], 0, v[210:211]
	s_andn2_b64 vcc, exec, s[38:39]
	s_nop 0
	global_store_dwordx4 v[194:195], v[140:143], off sc1
.Lmy_wt_g2b_4r:
	v_pk_fma_f32 v[138:139], v[138:139], v[106:107], v[186:187]
	v_pk_fma_f32 v[136:137], v[136:137], v[104:105], v[184:185]
	v_pk_mul_f32 v[142:143], v[114:115], v[146:147]
	v_pk_mul_f32 v[140:141], v[112:113], v[144:145]
	v_pk_mul_f32 v[144:145], v[110:111], v[190:191]
	v_pk_mul_f32 v[146:147], v[108:109], v[188:189]
	v_cvt_pk_bf16_f32 v140, v140, v141
	v_cvt_pk_bf16_f32 v141, v142, v143
	v_cvt_pk_bf16_f32 v143, v144, v145
	v_lshl_add_u64 v[144:145], s[22:23], 0, v[192:193]
	v_cvt_pk_bf16_f32 v142, v146, v147
	v_lshl_add_u64 v[144:145], v[144:145], 0, v[210:211]
	s_andn2_b64 vcc, exec, s[38:39]
	s_nop 0
	global_store_dwordx4 v[144:145], v[140:143], off sc1
.Lmy_wt_g2b_5r:
	v_readlane_b32 s8, v252, 7
	v_readlane_b32 s9, v252, 8
	v_pk_fma_f32 v[140:141], v[134:135], v[102:103], v[182:183]
	v_pk_fma_f32 v[142:143], v[132:133], v[100:101], v[180:181]
	v_pk_mul_f32 v[132:133], v[140:141], v[140:141]
	v_pk_mul_f32 v[134:135], v[142:143], v[142:143]
	v_pk_fma_f32 v[132:133], v[138:139], v[138:139], v[132:133]
	v_pk_fma_f32 v[134:135], v[136:137], v[136:137], v[134:135]
	v_add_f32_e32 v132, v132, v133
	v_add_f32_e32 v134, v134, v135
	v_add_f32_e32 v132, v134, v132
	v_add_f32_e32 v146, v200, v132
	v_cvt_pk_bf16_f32 v132, v136, v137
	v_cvt_pk_bf16_f32 v133, v138, v139
	v_cvt_pk_bf16_f32 v134, v142, v143
	v_cvt_pk_bf16_f32 v135, v140, v141
	s_andn2_b64 vcc, exec, s[38:39]
	s_nop 0
	global_store_dwordx4 v[194:195], v[132:135], off offset:256 sc1
.Lmy_wt_g2b_6r:
	ds_bpermute_b32 v135, v227, v146
	v_pk_mul_f32 v[138:139], v[92:93], v[138:139]
	v_pk_mul_f32 v[132:133], v[90:91], v[136:137]
	v_pk_mul_f32 v[140:141], v[88:89], v[140:141]
	v_cvt_pk_bf16_f32 v134, v132, v133
	s_waitcnt lgkmcnt(0)
	v_add_f32_e32 v132, v146, v135
	ds_bpermute_b32 v133, v226, v132
	v_pk_mul_f32 v[136:137], v[86:87], v[142:143]
	v_cvt_pk_bf16_f32 v135, v138, v139
	v_cvt_pk_bf16_f32 v136, v136, v137
	v_cvt_pk_bf16_f32 v137, v140, v141
	v_readlane_b32 s10, v252, 9
	v_readlane_b32 s11, v252, 10
	v_readlane_b32 s12, v252, 11
	v_readlane_b32 s13, v252, 12
	v_readlane_b32 s14, v252, 13
	v_readlane_b32 s15, v252, 14
	v_readlane_b32 s16, v252, 15
	v_readlane_b32 s17, v252, 16
	v_readlane_b32 s18, v252, 17
	v_readlane_b32 s19, v252, 18
	s_andn2_b64 vcc, exec, s[38:39]
	s_nop 0
	global_store_dwordx4 v[144:145], v[134:137], off offset:256 sc1

.LBB0_915:
	s_or_b64 exec, exec, s[68:69]
	s_movk_i32 s4, 0x3f80
	v_cmp_gt_i32_e32 vcc, s4, v214
	v_readlane_b32 s4, v252, 3
	v_add_u32_e32 v180, 0x80, v214
	v_readlane_b32 s5, v252, 4
	v_readlane_b32 s7, v252, 6
	v_ashrrev_i32_e32 v181, 31, v180
	v_add_u32_e32 v132, 0xffffc080, v214
	v_readlane_b32 s6, v252, 5
	v_mov_b32_e32 v134, s7
	v_mov_b32_e32 v135, s5
	s_waitcnt lgkmcnt(0)
	v_cndmask_b32_e32 v133, 0, v181, vcc
	v_cndmask_b32_e32 v132, v132, v180, vcc
	v_cndmask_b32_e32 v135, v134, v135, vcc
	v_mov_b32_e32 v134, s6
	v_mov_b32_e32 v136, s4
	v_cndmask_b32_e32 v134, v134, v136, vcc
	v_lshlrev_b64 v[132:133], 12, v[132:133]
	v_lshl_add_u64 v[132:133], v[134:135], 0, v[132:133]
	v_lshl_add_u64 v[136:137], v[212:213], 2, v[132:133]
	global_load_dwordx4 v[140:143], v[136:137], off offset:16
	global_load_dwordx4 v[144:147], v[136:137], off
	global_load_dwordx4 v[132:135], v[136:137], off offset:528
	s_nop 0
	global_load_dwordx4 v[136:139], v[136:137], off offset:512
	v_pk_fma_f32 v[174:175], v[122:123], v[118:119], v[174:175]
	v_pk_fma_f32 v[172:173], v[120:121], v[116:117], v[172:173]
	v_pk_fma_f32 v[130:131], v[130:131], v[126:127], v[178:179]
	v_pk_fma_f32 v[128:129], v[128:129], v[124:125], v[176:177]
	v_pk_mul_f32 v[120:121], v[174:175], v[174:175]
	v_pk_mul_f32 v[122:123], v[172:173], v[172:173]
	v_pk_fma_f32 v[120:121], v[130:131], v[130:131], v[120:121]
	v_pk_fma_f32 v[122:123], v[128:129], v[128:129], v[122:123]
	v_lshlrev_b64 v[176:177], 11, v[216:217]
	v_add_f32_e32 v122, v122, v123
	v_add_f32_e32 v120, v120, v121
	v_lshl_add_u64 v[178:179], s[82:83], 0, v[176:177]
	v_add_f32_e32 v182, v122, v120
	v_cvt_pk_bf16_f32 v120, v128, v129
	v_cvt_pk_bf16_f32 v121, v130, v131
	v_cvt_pk_bf16_f32 v122, v172, v173
	v_cvt_pk_bf16_f32 v123, v174, v175
	v_lshl_add_u64 v[178:179], v[178:179], 0, v[210:211]
	s_andn2_b64 vcc, exec, s[38:39]
	s_nop 0
	global_store_dwordx4 v[178:179], v[120:123], off sc1
.Lmy_wt_g2b_8r:
	v_pk_fma_f32 v[96:97], v[96:97], v[106:107], v[170:171]
	v_pk_fma_f32 v[94:95], v[94:95], v[104:105], v[168:169]
	v_pk_mul_f32 v[122:123], v[114:115], v[130:131]
	v_pk_mul_f32 v[120:121], v[112:113], v[128:129]
	v_pk_mul_f32 v[128:129], v[110:111], v[174:175]
	v_pk_mul_f32 v[130:131], v[108:109], v[172:173]
	v_cvt_pk_bf16_f32 v120, v120, v121
	v_cvt_pk_bf16_f32 v121, v122, v123
	v_cvt_pk_bf16_f32 v123, v128, v129
	v_lshl_add_u64 v[128:129], s[22:23], 0, v[176:177]
	v_cvt_pk_bf16_f32 v122, v130, v131
	v_lshl_add_u64 v[128:129], v[128:129], 0, v[210:211]
	s_andn2_b64 vcc, exec, s[38:39]
	s_nop 0
	global_store_dwordx4 v[128:129], v[120:123], off sc1
.Lmy_wt_g2b_9r:
	v_readlane_b32 s8, v252, 7
	v_readlane_b32 s9, v252, 8
	v_pk_fma_f32 v[120:121], v[84:85], v[102:103], v[166:167]
	v_pk_fma_f32 v[122:123], v[82:83], v[100:101], v[164:165]
	v_pk_mul_f32 v[82:83], v[120:121], v[120:121]
	v_pk_mul_f32 v[84:85], v[122:123], v[122:123]
	v_pk_fma_f32 v[82:83], v[96:97], v[96:97], v[82:83]
	v_pk_fma_f32 v[84:85], v[94:95], v[94:95], v[84:85]
	v_add_f32_e32 v82, v82, v83
	v_add_f32_e32 v84, v84, v85
	v_add_f32_e32 v82, v84, v82
	v_add_f32_e32 v130, v182, v82
	ds_bpermute_b32 v131, v227, v130
	v_cvt_pk_bf16_f32 v82, v94, v95
	v_cvt_pk_bf16_f32 v83, v96, v97
	v_cvt_pk_bf16_f32 v84, v122, v123
	v_cvt_pk_bf16_f32 v85, v120, v121
	s_andn2_b64 vcc, exec, s[38:39]
	s_nop 0
	global_store_dwordx4 v[178:179], v[82:85], off offset:256 sc1
.Lmy_wt_g2b_10r:
	v_pk_mul_f32 v[120:121], v[88:89], v[120:121]
	v_readlane_b32 s10, v252, 9
	v_pk_mul_f32 v[82:83], v[90:91], v[94:95]
	v_pk_mul_f32 v[84:85], v[92:93], v[96:97]
	v_cvt_pk_bf16_f32 v94, v82, v83
	s_waitcnt lgkmcnt(0)
	v_add_f32_e32 v82, v130, v131
	ds_bpermute_b32 v83, v226, v82
	v_pk_mul_f32 v[96:97], v[86:87], v[122:123]
	v_cvt_pk_bf16_f32 v95, v84, v85
	v_cvt_pk_bf16_f32 v96, v96, v97
	v_cvt_pk_bf16_f32 v97, v120, v121
	v_readlane_b32 s11, v252, 10
	v_readlane_b32 s12, v252, 11
	v_readlane_b32 s13, v252, 12
	v_readlane_b32 s14, v252, 13
	v_readlane_b32 s15, v252, 14
	v_readlane_b32 s16, v252, 15
	v_readlane_b32 s17, v252, 16
	v_readlane_b32 s18, v252, 17
	v_readlane_b32 s19, v252, 18
	s_andn2_b64 vcc, exec, s[38:39]
	s_nop 0
	global_store_dwordx4 v[128:129], v[94:97], off offset:256 sc1

.LBB0_917:
	s_or_b64 exec, exec, s[68:69]
	s_movk_i32 s4, 0x3f70
	v_cmp_gt_i32_e32 vcc, s4, v214
	v_readlane_b32 s4, v252, 3
	v_add_u32_e32 v82, 0x90, v214
	v_add_u32_e32 v84, 0xffffc090, v214
	v_readlane_b32 s5, v252, 4
	v_readlane_b32 s7, v252, 6
	s_waitcnt lgkmcnt(0)
	v_ashrrev_i32_e32 v83, 31, v82
	v_cndmask_b32_e32 v82, v84, v82, vcc
	v_readlane_b32 s6, v252, 5
	v_mov_b32_e32 v84, s7
	v_mov_b32_e32 v85, s5
	v_cndmask_b32_e32 v83, 0, v83, vcc
	v_cndmask_b32_e32 v85, v84, v85, vcc
	v_mov_b32_e32 v84, s6
	v_mov_b32_e32 v94, s4
	v_cndmask_b32_e32 v84, v84, v94, vcc
	v_lshlrev_b64 v[82:83], 12, v[82:83]
	v_lshl_add_u64 v[82:83], v[84:85], 0, v[82:83]
	v_lshl_add_u64 v[94:95], v[212:213], 2, v[82:83]
	global_load_dwordx4 v[120:123], v[94:95], off offset:16
	global_load_dwordx4 v[128:131], v[94:95], off
	global_load_dwordx4 v[82:85], v[94:95], off offset:528
	s_nop 0
	global_load_dwordx4 v[94:97], v[94:95], off offset:512
	s_waitcnt vmcnt(19)
	v_pk_fma_f32 v[158:159], v[76:77], v[118:119], v[158:159]
	v_pk_fma_f32 v[156:157], v[74:75], v[116:117], v[156:157]
	s_waitcnt vmcnt(18)
	v_pk_fma_f32 v[80:81], v[80:81], v[126:127], v[162:163]
	v_pk_fma_f32 v[78:79], v[78:79], v[124:125], v[160:161]
	v_pk_mul_f32 v[74:75], v[158:159], v[158:159]
	v_pk_mul_f32 v[76:77], v[156:157], v[156:157]
	v_pk_fma_f32 v[74:75], v[80:81], v[80:81], v[74:75]
	v_pk_fma_f32 v[76:77], v[78:79], v[78:79], v[76:77]
	v_lshlrev_b64 v[160:161], 11, v[218:219]
	v_add_f32_e32 v76, v76, v77
	v_add_f32_e32 v74, v74, v75
	v_lshl_add_u64 v[162:163], s[82:83], 0, v[160:161]
	v_add_f32_e32 v164, v76, v74
	v_cvt_pk_bf16_f32 v74, v78, v79
	v_cvt_pk_bf16_f32 v75, v80, v81
	v_cvt_pk_bf16_f32 v76, v156, v157
	v_cvt_pk_bf16_f32 v77, v158, v159
	v_lshl_add_u64 v[162:163], v[162:163], 0, v[210:211]
	s_andn2_b64 vcc, exec, s[38:39]
	s_nop 0
	global_store_dwordx4 v[162:163], v[74:77], off sc1
.Lmy_wt_g2b_12r:
	s_waitcnt vmcnt(17)
	v_pk_fma_f32 v[72:73], v[72:73], v[106:107], v[154:155]
	v_pk_fma_f32 v[70:71], v[70:71], v[104:105], v[152:153]
	v_pk_mul_f32 v[76:77], v[114:115], v[80:81]
	v_pk_mul_f32 v[74:75], v[112:113], v[78:79]
	v_pk_mul_f32 v[78:79], v[110:111], v[158:159]
	v_pk_mul_f32 v[80:81], v[108:109], v[156:157]
	v_cvt_pk_bf16_f32 v74, v74, v75
	v_cvt_pk_bf16_f32 v75, v76, v77
	v_cvt_pk_bf16_f32 v77, v78, v79
	v_lshl_add_u64 v[78:79], s[22:23], 0, v[160:161]
	v_cvt_pk_bf16_f32 v76, v80, v81
	v_lshl_add_u64 v[78:79], v[78:79], 0, v[210:211]
	s_andn2_b64 vcc, exec, s[38:39]
	s_nop 0
	global_store_dwordx4 v[78:79], v[74:77], off sc1
.Lmy_wt_g2b_13r:
	v_readlane_b32 s8, v252, 7
	v_readlane_b32 s9, v252, 8
	v_pk_fma_f32 v[74:75], v[68:69], v[102:103], v[150:151]
	v_pk_fma_f32 v[76:77], v[66:67], v[100:101], v[148:149]
	v_pk_mul_f32 v[66:67], v[74:75], v[74:75]
	v_pk_mul_f32 v[68:69], v[76:77], v[76:77]
	v_pk_fma_f32 v[66:67], v[72:73], v[72:73], v[66:67]
	v_pk_fma_f32 v[68:69], v[70:71], v[70:71], v[68:69]
	v_add_f32_e32 v66, v66, v67
	v_add_f32_e32 v68, v68, v69
	v_add_f32_e32 v66, v68, v66
	v_add_f32_e32 v80, v164, v66
	v_cvt_pk_bf16_f32 v66, v70, v71
	v_cvt_pk_bf16_f32 v67, v72, v73
	v_cvt_pk_bf16_f32 v68, v76, v77
	v_cvt_pk_bf16_f32 v69, v74, v75
	s_andn2_b64 vcc, exec, s[38:39]
	s_nop 0
	global_store_dwordx4 v[162:163], v[66:69], off offset:256 sc1
.Lmy_wt_g2b_14r:
	ds_bpermute_b32 v69, v227, v80
	v_pk_mul_f32 v[72:73], v[92:93], v[72:73]
	v_pk_mul_f32 v[66:67], v[90:91], v[70:71]
	v_pk_mul_f32 v[74:75], v[88:89], v[74:75]
	v_cvt_pk_bf16_f32 v68, v66, v67
	s_waitcnt lgkmcnt(0)
	v_add_f32_e32 v66, v80, v69
	ds_bpermute_b32 v67, v226, v66
	v_pk_mul_f32 v[70:71], v[86:87], v[76:77]
	v_cvt_pk_bf16_f32 v69, v72, v73
	v_cvt_pk_bf16_f32 v70, v70, v71
	v_cvt_pk_bf16_f32 v71, v74, v75
	v_readlane_b32 s10, v252, 9
	v_readlane_b32 s11, v252, 10
	v_readlane_b32 s12, v252, 11
	v_readlane_b32 s13, v252, 12
	v_readlane_b32 s14, v252, 13
	v_readlane_b32 s15, v252, 14
	v_readlane_b32 s16, v252, 15
	v_readlane_b32 s17, v252, 16
	v_readlane_b32 s18, v252, 17
	v_readlane_b32 s19, v252, 18
	s_andn2_b64 vcc, exec, s[38:39]
	s_nop 0
	global_store_dwordx4 v[78:79], v[68:71], off offset:256 sc1

.LBB0_1119:
	s_lshl_b32 s4, s70, 8
	v_add_u32_e32 v194, s4, v204
	s_addk_i32 s4, 0xc000
	s_lshr_b32 s4, s4, 12
	s_ashr_i32 s5, s70, 5
	s_add_i32 s4, s4, 2
	s_cmp_lt_i32 s70, 64
	v_lshl_or_b32 v178, s20, 8, v206
	s_cselect_b32 s4, s5, s4
	v_ashrrev_i32_e32 v179, 31, v178
	s_ashr_i32 s5, s4, 31
	v_lshlrev_b64 v[180:181], 1, v[178:179]
	v_ashrrev_i32_e32 v195, 31, v194
	s_lshl_b64 s[4:5], s[4:5], 14
	v_lshl_add_u64 v[148:149], s[82:83], 0, v[180:181]
	v_lshlrev_b64 v[214:215], 11, v[194:195]
	s_add_u32 s4, s89, s4
	v_lshl_add_u64 v[112:113], v[148:149], 0, v[214:215]
	s_addc_u32 s5, s90, s5
	global_load_dwordx4 v[200:203], v[112:113], off
	global_load_dwordx4 v[210:213], v[112:113], off offset:256
	v_lshl_add_u64 v[112:113], v[178:179], 2, s[4:5]
	global_load_dwordx4 v[128:131], v[112:113], off
	global_load_dwordx4 v[124:127], v[112:113], off offset:16
	global_load_dwordx4 v[116:119], v[112:113], off offset:512
	s_nop 0
	global_load_dwordx4 v[112:115], v[112:113], off offset:528
	v_or_b32_e32 v190, 16, v194
	v_or_b32_e32 v186, 32, v194
	v_or_b32_e32 v182, 48, v194
	v_ashrrev_i32_e32 v191, 31, v190
	v_ashrrev_i32_e32 v187, 31, v186
	v_ashrrev_i32_e32 v183, 31, v182
	v_lshlrev_b64 v[192:193], 11, v[190:191]
	v_lshlrev_b64 v[188:189], 11, v[186:187]
	v_lshlrev_b64 v[184:185], 11, v[182:183]
	v_lshl_add_u64 v[150:151], v[148:149], 0, v[192:193]
	v_lshl_add_u64 v[152:153], v[148:149], 0, v[188:189]
	v_lshl_add_u64 v[148:149], v[148:149], 0, v[184:185]
	global_load_dwordx4 v[168:171], v[150:151], off
	global_load_dwordx4 v[164:167], v[150:151], off offset:256
	global_load_dwordx4 v[160:163], v[152:153], off
	global_load_dwordx4 v[156:159], v[152:153], off offset:256
	s_nop 0
	global_load_dwordx4 v[152:155], v[148:149], off
	s_nop 0
	global_load_dwordx4 v[148:151], v[148:149], off offset:256
	v_and_b32_e32 v209, 64, v229
	v_xor_b32_e32 v208, 16, v229
	v_add_u32_e32 v209, 64, v209
	v_xor_b32_e32 v216, 32, v229
	v_cmp_lt_i32_e32 vcc, v208, v209
	s_lshl_b32 s20, s20, 2
	s_ashr_i32 s21, s20, 31
	v_cndmask_b32_e32 v208, v229, v208, vcc
	v_cmp_lt_i32_e32 vcc, v216, v209
	v_lshlrev_b32_e32 v209, 2, v208
	s_waitcnt vmcnt(0)
	v_and_b32_e32 v217, 0xffff0000, v200
	v_cndmask_b32_e32 v216, v229, v216, vcc
	s_andn2_b64 vcc, exec, s[30:31]
	v_lshlrev_b32_e32 v208, 2, v216
	v_lshlrev_b32_e32 v216, 16, v200
	v_lshlrev_b32_e32 v200, 16, v201
	v_and_b32_e32 v201, 0xffff0000, v201
	v_lshlrev_b32_e32 v218, 16, v202
	v_and_b32_e32 v219, 0xffff0000, v202
	v_lshlrev_b32_e32 v202, 16, v203
	v_and_b32_e32 v203, 0xffff0000, v203
	v_lshlrev_b32_e32 v222, 16, v212
	v_and_b32_e32 v223, 0xffff0000, v212
	v_lshlrev_b32_e32 v212, 16, v213
	v_and_b32_e32 v213, 0xffff0000, v213
	v_lshlrev_b32_e32 v220, 16, v210
	v_and_b32_e32 v221, 0xffff0000, v210
	v_lshlrev_b32_e32 v210, 16, v211
	v_and_b32_e32 v211, 0xffff0000, v211
	v_pk_fma_f32 v[146:147], v[146:147], v[130:131], v[200:201]
	v_pk_fma_f32 v[142:143], v[142:143], v[126:127], v[202:203]
	v_pk_fma_f32 v[140:141], v[140:141], v[124:125], v[218:219]
	v_pk_fma_f32 v[200:201], v[134:135], v[114:115], v[212:213]
	v_pk_fma_f32 v[202:203], v[132:133], v[112:113], v[222:223]
	v_pk_fma_f32 v[144:145], v[144:145], v[128:129], v[216:217]
	v_pk_fma_f32 v[136:137], v[136:137], v[116:117], v[220:221]
	v_pk_fma_f32 v[138:139], v[138:139], v[118:119], v[210:211]
	v_pk_mul_f32 v[210:211], v[140:141], v[140:141]
	v_pk_mul_f32 v[212:213], v[142:143], v[142:143]
	v_cvt_pk_bf16_f32 v134, v140, v141
	v_cvt_pk_bf16_f32 v135, v142, v143
	v_pk_mul_f32 v[140:141], v[202:203], v[202:203]
	v_pk_mul_f32 v[142:143], v[200:201], v[200:201]
	v_cvt_pk_bf16_f32 v132, v144, v145
	v_cvt_pk_bf16_f32 v133, v146, v147
	v_pk_fma_f32 v[146:147], v[146:147], v[146:147], v[212:213]
	v_pk_fma_f32 v[144:145], v[144:145], v[144:145], v[210:211]
	v_pk_fma_f32 v[142:143], v[138:139], v[138:139], v[142:143]
	v_pk_fma_f32 v[140:141], v[136:137], v[136:137], v[140:141]
	v_add_f32_e32 v144, v144, v145
	v_add_f32_e32 v145, v146, v147
	v_add_f32_e32 v140, v140, v141
	v_add_f32_e32 v142, v142, v143
	v_add_f32_e32 v141, v144, v145
	v_add_f32_e32 v140, v140, v142
	v_add_f32_e32 v142, v141, v140
	ds_bpermute_b32 v143, v209, v142
	v_lshl_add_u64 v[140:141], s[22:23], 0, v[214:215]
	v_lshl_add_u64 v[140:141], v[140:141], 0, v[180:181]
	s_nop 0
	global_store_dwordx4 v[140:141], v[132:135], off sc1
.Lmy_wt_g4a_0r:
	s_waitcnt lgkmcnt(0)
	s_nop 0
	v_add_f32_e32 v132, v142, v143
	ds_bpermute_b32 v133, v208, v132
	v_cvt_pk_bf16_f32 v134, v136, v137
	v_cvt_pk_bf16_f32 v135, v138, v139
	v_cvt_pk_bf16_f32 v136, v202, v203
	v_cvt_pk_bf16_f32 v137, v200, v201
	s_nop 0
	global_store_dwordx4 v[140:141], v[134:137], off offset:256 sc1

.LBB0_1121:
	s_or_b64 exec, exec, s[70:71]
	v_add_u32_e32 v140, 0x80, v194
	v_ashrrev_i32_e32 v141, 31, v140
	v_lshlrev_b64 v[142:143], 11, v[140:141]
	s_waitcnt lgkmcnt(0)
	v_lshl_add_u64 v[132:133], s[82:83], 0, v[142:143]
	v_lshl_add_u64 v[132:133], v[132:133], 0, v[180:181]
	global_load_dwordx4 v[136:139], v[132:133], off
	s_nop 0
	global_load_dwordx4 v[132:135], v[132:133], off offset:256
	v_lshlrev_b32_e32 v144, 16, v168
	v_and_b32_e32 v145, 0xffff0000, v168
	v_lshlrev_b32_e32 v146, 16, v169
	v_and_b32_e32 v147, 0xffff0000, v169
	v_lshlrev_b32_e32 v168, 16, v170
	v_and_b32_e32 v169, 0xffff0000, v170
	v_lshlrev_b32_e32 v170, 16, v171
	v_and_b32_e32 v171, 0xffff0000, v171
	v_pk_fma_f32 v[120:121], v[120:121], v[128:129], v[144:145]
	v_pk_fma_f32 v[144:145], v[110:111], v[126:127], v[170:171]
	v_pk_fma_f32 v[110:111], v[108:109], v[124:125], v[168:169]
	v_pk_fma_f32 v[122:123], v[122:123], v[130:131], v[146:147]
	v_pk_mul_f32 v[108:109], v[110:111], v[110:111]
	v_pk_mul_f32 v[146:147], v[144:145], v[144:145]
	v_pk_fma_f32 v[108:109], v[120:121], v[120:121], v[108:109]
	v_pk_fma_f32 v[146:147], v[122:123], v[122:123], v[146:147]
	v_add_f32_e32 v108, v108, v109
	v_add_f32_e32 v109, v146, v147
	v_add_f32_e32 v168, v108, v109
	v_cvt_pk_bf16_f32 v108, v120, v121
	v_cvt_pk_bf16_f32 v109, v122, v123
	v_cvt_pk_bf16_f32 v110, v110, v111
	v_cvt_pk_bf16_f32 v111, v144, v145
	v_lshlrev_b32_e32 v120, 16, v164
	v_and_b32_e32 v121, 0xffff0000, v164
	v_lshlrev_b32_e32 v122, 16, v165
	v_and_b32_e32 v123, 0xffff0000, v165
	v_lshlrev_b32_e32 v144, 16, v166
	v_and_b32_e32 v145, 0xffff0000, v166
	v_lshlrev_b32_e32 v146, 16, v167
	v_and_b32_e32 v147, 0xffff0000, v167
	v_pk_fma_f32 v[104:105], v[104:105], v[116:117], v[120:121]
	v_pk_fma_f32 v[106:107], v[106:107], v[118:119], v[122:123]
	v_pk_fma_f32 v[120:121], v[102:103], v[114:115], v[146:147]
	v_pk_fma_f32 v[122:123], v[100:101], v[112:113], v[144:145]
	v_pk_mul_f32 v[102:103], v[120:121], v[120:121]
	v_pk_mul_f32 v[100:101], v[122:123], v[122:123]
	v_pk_fma_f32 v[102:103], v[106:107], v[106:107], v[102:103]
	v_pk_fma_f32 v[100:101], v[104:105], v[104:105], v[100:101]
	s_nop 0
	v_add_f32_e32 v100, v100, v101
	v_add_f32_e32 v101, v102, v103
	v_add_f32_e32 v100, v100, v101
	v_add_f32_e32 v103, v168, v100
	ds_bpermute_b32 v146, v209, v103
	v_lshl_add_u64 v[100:101], s[22:23], 0, v[192:193]
	v_lshl_add_u64 v[144:145], v[100:101], 0, v[180:181]
	v_cvt_pk_bf16_f32 v102, v104, v105
	v_cvt_pk_bf16_f32 v104, v122, v123
	s_waitcnt lgkmcnt(0)
	v_add_f32_e32 v100, v103, v146
	ds_bpermute_b32 v101, v208, v100
	v_cvt_pk_bf16_f32 v103, v106, v107
	v_cvt_pk_bf16_f32 v105, v120, v121
	s_nop 0
	global_store_dwordx4 v[144:145], v[108:111], off sc1
.Lmy_wt_g4a_2r:
	s_nop 0
	global_store_dwordx4 v[144:145], v[102:105], off offset:256 sc1

.LBB0_1123:
	s_or_b64 exec, exec, s[70:71]
	v_or_b32_e32 v108, 16, v140
	v_ashrrev_i32_e32 v109, 31, v108
	v_lshlrev_b64 v[110:111], 11, v[108:109]
	s_waitcnt lgkmcnt(0)
	v_lshl_add_u64 v[100:101], s[82:83], 0, v[110:111]
	v_lshl_add_u64 v[100:101], v[100:101], 0, v[180:181]
	global_load_dwordx4 v[104:107], v[100:101], off
	s_nop 0
	global_load_dwordx4 v[100:103], v[100:101], off offset:256
	v_lshlrev_b32_e32 v120, 16, v160
	v_and_b32_e32 v121, 0xffff0000, v160
	v_lshlrev_b32_e32 v144, 16, v162
	v_and_b32_e32 v145, 0xffff0000, v162
	v_lshlrev_b32_e32 v146, 16, v163
	v_and_b32_e32 v147, 0xffff0000, v163
	v_lshlrev_b32_e32 v122, 16, v161
	v_and_b32_e32 v123, 0xffff0000, v161
	v_pk_fma_f32 v[94:95], v[94:95], v[128:129], v[120:121]
	v_pk_fma_f32 v[120:121], v[92:93], v[126:127], v[146:147]
	v_pk_fma_f32 v[92:93], v[90:91], v[124:125], v[144:145]
	v_pk_fma_f32 v[96:97], v[96:97], v[130:131], v[122:123]
	v_pk_mul_f32 v[90:91], v[92:93], v[92:93]
	v_pk_mul_f32 v[122:123], v[120:121], v[120:121]
	v_pk_fma_f32 v[90:91], v[94:95], v[94:95], v[90:91]
	v_pk_fma_f32 v[122:123], v[96:97], v[96:97], v[122:123]
	v_add_f32_e32 v90, v90, v91
	v_add_f32_e32 v91, v122, v123
	v_add_f32_e32 v144, v90, v91
	v_cvt_pk_bf16_f32 v90, v94, v95
	v_cvt_pk_bf16_f32 v91, v96, v97
	v_cvt_pk_bf16_f32 v92, v92, v93
	v_cvt_pk_bf16_f32 v93, v120, v121
	v_lshlrev_b32_e32 v94, 16, v156
	v_and_b32_e32 v95, 0xffff0000, v156
	v_lshlrev_b32_e32 v96, 16, v157
	v_and_b32_e32 v97, 0xffff0000, v157
	v_lshlrev_b32_e32 v120, 16, v158
	v_and_b32_e32 v121, 0xffff0000, v158
	v_lshlrev_b32_e32 v122, 16, v159
	v_and_b32_e32 v123, 0xffff0000, v159
	v_pk_fma_f32 v[86:87], v[86:87], v[116:117], v[94:95]
	v_pk_fma_f32 v[88:89], v[88:89], v[118:119], v[96:97]
	v_pk_fma_f32 v[94:95], v[84:85], v[114:115], v[122:123]
	v_pk_fma_f32 v[96:97], v[82:83], v[112:113], v[120:121]
	v_pk_mul_f32 v[84:85], v[94:95], v[94:95]
	v_pk_mul_f32 v[82:83], v[96:97], v[96:97]
	v_pk_fma_f32 v[84:85], v[88:89], v[88:89], v[84:85]
	v_pk_fma_f32 v[82:83], v[86:87], v[86:87], v[82:83]
	s_nop 0
	v_add_f32_e32 v82, v82, v83
	v_add_f32_e32 v83, v84, v85
	v_add_f32_e32 v82, v82, v83
	v_add_f32_e32 v85, v144, v82
	ds_bpermute_b32 v122, v209, v85
	v_lshl_add_u64 v[82:83], s[22:23], 0, v[188:189]
	v_lshl_add_u64 v[120:121], v[82:83], 0, v[180:181]
	v_cvt_pk_bf16_f32 v84, v86, v87
	v_cvt_pk_bf16_f32 v86, v96, v97
	s_waitcnt lgkmcnt(0)
	v_add_f32_e32 v82, v85, v122
	ds_bpermute_b32 v83, v208, v82
	v_cvt_pk_bf16_f32 v85, v88, v89
	v_cvt_pk_bf16_f32 v87, v94, v95
	s_nop 0
	global_store_dwordx4 v[120:121], v[90:93], off sc1
.Lmy_wt_g4a_4r:
	s_nop 0
	global_store_dwordx4 v[120:121], v[84:87], off offset:256 sc1

.LBB0_1125:
	s_or_b64 exec, exec, s[70:71]
	v_or_b32_e32 v90, 32, v140
	v_ashrrev_i32_e32 v91, 31, v90
	v_lshlrev_b64 v[92:93], 11, v[90:91]
	s_waitcnt lgkmcnt(0)
	v_lshl_add_u64 v[82:83], s[82:83], 0, v[92:93]
	v_lshl_add_u64 v[82:83], v[82:83], 0, v[180:181]
	global_load_dwordx4 v[86:89], v[82:83], off
	s_nop 0
	global_load_dwordx4 v[82:85], v[82:83], off offset:256
	v_lshlrev_b32_e32 v94, 16, v152
	v_and_b32_e32 v95, 0xffff0000, v152
	v_lshlrev_b32_e32 v120, 16, v154
	v_and_b32_e32 v121, 0xffff0000, v154
	v_lshlrev_b32_e32 v122, 16, v155
	v_and_b32_e32 v123, 0xffff0000, v155
	v_lshlrev_b32_e32 v96, 16, v153
	v_and_b32_e32 v97, 0xffff0000, v153
	v_pk_fma_f32 v[78:79], v[78:79], v[128:129], v[94:95]
	v_pk_fma_f32 v[94:95], v[76:77], v[126:127], v[122:123]
	v_pk_fma_f32 v[76:77], v[74:75], v[124:125], v[120:121]
	v_pk_fma_f32 v[80:81], v[80:81], v[130:131], v[96:97]
	v_pk_mul_f32 v[74:75], v[76:77], v[76:77]
	v_pk_mul_f32 v[96:97], v[94:95], v[94:95]
	v_pk_fma_f32 v[74:75], v[78:79], v[78:79], v[74:75]
	v_pk_fma_f32 v[96:97], v[80:81], v[80:81], v[96:97]
	v_add_f32_e32 v74, v74, v75
	v_add_f32_e32 v75, v96, v97
	v_add_f32_e32 v120, v74, v75
	v_cvt_pk_bf16_f32 v74, v78, v79
	v_cvt_pk_bf16_f32 v75, v80, v81
	v_cvt_pk_bf16_f32 v76, v76, v77
	v_cvt_pk_bf16_f32 v77, v94, v95
	v_lshlrev_b32_e32 v78, 16, v148
	v_and_b32_e32 v79, 0xffff0000, v148
	v_lshlrev_b32_e32 v80, 16, v149
	v_and_b32_e32 v81, 0xffff0000, v149
	v_lshlrev_b32_e32 v94, 16, v150
	v_and_b32_e32 v95, 0xffff0000, v150
	v_lshlrev_b32_e32 v96, 16, v151
	v_and_b32_e32 v97, 0xffff0000, v151
	v_pk_fma_f32 v[70:71], v[70:71], v[116:117], v[78:79]
	v_pk_fma_f32 v[72:73], v[72:73], v[118:119], v[80:81]
	v_pk_fma_f32 v[78:79], v[68:69], v[114:115], v[96:97]
	v_pk_fma_f32 v[80:81], v[66:67], v[112:113], v[94:95]
	v_pk_mul_f32 v[68:69], v[78:79], v[78:79]
	v_pk_mul_f32 v[66:67], v[80:81], v[80:81]
	v_pk_fma_f32 v[68:69], v[72:73], v[72:73], v[68:69]
	v_pk_fma_f32 v[66:67], v[70:71], v[70:71], v[66:67]
	s_nop 0
	v_add_f32_e32 v66, v66, v67
	v_add_f32_e32 v67, v68, v69
	v_add_f32_e32 v66, v66, v67
	v_add_f32_e32 v69, v120, v66
	ds_bpermute_b32 v96, v209, v69
	v_lshl_add_u64 v[66:67], s[22:23], 0, v[184:185]
	v_lshl_add_u64 v[94:95], v[66:67], 0, v[180:181]
	v_cvt_pk_bf16_f32 v68, v70, v71
	v_cvt_pk_bf16_f32 v70, v80, v81
	s_waitcnt lgkmcnt(0)
	v_add_f32_e32 v66, v69, v96
	ds_bpermute_b32 v67, v208, v66
	v_cvt_pk_bf16_f32 v69, v72, v73
	v_cvt_pk_bf16_f32 v71, v78, v79
	s_nop 0
	global_store_dwordx4 v[94:95], v[74:77], off sc1
.Lmy_wt_g4a_6r:
	s_nop 0
	global_store_dwordx4 v[94:95], v[68:71], off offset:256 sc1

.LBB0_1175:
	s_lshl_b32 s6, s68, 8
	s_add_i32 s5, s6, 0xffffc000
	s_lshr_b32 s5, s5, 12
	s_ashr_i32 s4, s68, 5
	s_add_i32 s5, s5, 2
	s_cmp_lt_i32 s68, 64
	s_cselect_b32 s4, s4, s5
	s_ashr_i32 s5, s4, 31
	s_lshl_b64 s[4:5], s[4:5], 14
	v_lshl_or_b32 v164, s56, 8, v240
	s_add_u32 s44, s89, s4
	s_addc_u32 s45, s90, s5
	v_ashrrev_i32_e32 v165, 31, v164
	v_add_u32_e32 v222, s6, v238
	s_add_u32 s4, s8, s4
	v_lshlrev_b64 v[210:211], 1, v[164:165]
	v_ashrrev_i32_e32 v223, 31, v222
	v_lshlrev_b64 v[90:91], 2, v[164:165]
	s_addc_u32 s5, s9, s5
	v_lshl_add_u64 v[164:165], s[82:83], 0, v[210:211]
	v_lshlrev_b64 v[226:227], 11, v[222:223]
	v_lshl_add_u64 v[92:93], s[44:45], 0, v[90:91]
	v_lshl_add_u64 v[94:95], s[4:5], 0, v[90:91]
	v_lshl_add_u64 v[166:167], v[164:165], 0, v[226:227]
	global_load_dwordx4 v[120:123], v[92:93], off offset:16
	global_load_dwordx4 v[128:131], v[92:93], off
	global_load_dwordx4 v[108:111], v[94:95], off offset:16
	global_load_dwordx4 v[112:115], v[94:95], off
	global_load_dwordx4 v[100:103], v[92:93], off offset:528
	global_load_dwordx4 v[104:107], v[92:93], off offset:512
	s_nop 0
	global_load_dwordx4 v[90:93], v[94:95], off offset:528
	s_nop 0
	global_load_dwordx4 v[94:97], v[94:95], off offset:512
	s_nop 0
	global_load_dwordx4 v[192:195], v[166:167], off
	global_load_dwordx4 v[188:191], v[166:167], off offset:256
	v_or_b32_e32 v220, 16, v222
	v_ashrrev_i32_e32 v221, 31, v220
	v_or_b32_e32 v216, 32, v222
	v_or_b32_e32 v212, 48, v222
	v_lshlrev_b64 v[224:225], 11, v[220:221]
	v_ashrrev_i32_e32 v217, 31, v216
	v_ashrrev_i32_e32 v213, 31, v212
	v_lshl_add_u64 v[166:167], v[164:165], 0, v[224:225]
	v_lshlrev_b64 v[218:219], 11, v[216:217]
	v_lshlrev_b64 v[214:215], 11, v[212:213]
	global_load_dwordx4 v[184:187], v[166:167], off
	global_load_dwordx4 v[180:183], v[166:167], off offset:256
	v_lshl_add_u64 v[166:167], v[164:165], 0, v[218:219]
	v_lshl_add_u64 v[164:165], v[164:165], 0, v[214:215]
	global_load_dwordx4 v[176:179], v[166:167], off
	global_load_dwordx4 v[172:175], v[166:167], off offset:256
	global_load_dwordx4 v[168:171], v[164:165], off
	s_nop 0
	global_load_dwordx4 v[164:167], v[164:165], off offset:256
	v_and_b32_e32 v201, 64, v229
	v_xor_b32_e32 v200, 16, v229
	v_add_u32_e32 v201, 64, v201
	v_cmp_lt_i32_e32 vcc, v200, v201
	s_lshl_b32 s56, s56, 2
	s_ashr_i32 s57, s56, 31
	v_cndmask_b32_e32 v200, v229, v200, vcc
	v_lshlrev_b32_e32 v242, 2, v200
	v_xor_b32_e32 v200, 32, v229
	v_cmp_lt_i32_e32 vcc, v200, v201
	s_waitcnt vmcnt(0)
	v_and_b32_e32 v201, 0xffff0000, v192
	v_cndmask_b32_e32 v200, v229, v200, vcc
	s_andn2_b64 vcc, exec, s[30:31]
	v_lshlrev_b32_e32 v243, 2, v200
	v_lshlrev_b32_e32 v200, 16, v192
	v_lshlrev_b32_e32 v192, 16, v193
	v_and_b32_e32 v193, 0xffff0000, v193
	v_lshlrev_b32_e32 v202, 16, v194
	v_and_b32_e32 v203, 0xffff0000, v194
	v_lshlrev_b32_e32 v194, 16, v195
	v_and_b32_e32 v195, 0xffff0000, v195
	v_pk_fma_f32 v[162:163], v[162:163], v[130:131], v[192:193]
	v_pk_fma_f32 v[192:193], v[158:159], v[122:123], v[194:195]
	v_pk_fma_f32 v[194:195], v[156:157], v[120:121], v[202:203]
	v_pk_fma_f32 v[160:161], v[160:161], v[128:129], v[200:201]
	v_pk_mul_f32 v[156:157], v[194:195], v[194:195]
	v_pk_mul_f32 v[158:159], v[192:193], v[192:193]
	v_pk_fma_f32 v[156:157], v[160:161], v[160:161], v[156:157]
	v_pk_fma_f32 v[158:159], v[162:163], v[162:163], v[158:159]
	v_add_f32_e32 v156, v156, v157
	v_add_f32_e32 v157, v158, v159
	v_lshl_add_u64 v[200:201], s[82:83], 0, v[226:227]
	v_add_f32_e32 v202, v156, v157
	v_cvt_pk_bf16_f32 v156, v160, v161
	v_cvt_pk_bf16_f32 v157, v162, v163
	v_cvt_pk_bf16_f32 v158, v194, v195
	v_cvt_pk_bf16_f32 v159, v192, v193
	v_lshl_add_u64 v[200:201], v[200:201], 0, v[210:211]
	s_nop 0
	global_store_dwordx4 v[200:201], v[156:159], off sc1

.LBB0_1177:
	s_or_b64 exec, exec, s[68:69]
	v_add_u32_e32 v156, 0x80, v222
	v_ashrrev_i32_e32 v157, 31, v156
	v_lshlrev_b64 v[160:161], 11, v[156:157]
	s_waitcnt lgkmcnt(0)
	v_lshl_add_u64 v[148:149], s[82:83], 0, v[160:161]
	v_lshl_add_u64 v[158:159], v[148:149], 0, v[210:211]
	global_load_dwordx4 v[152:155], v[158:159], off
	global_load_dwordx4 v[148:151], v[158:159], off offset:256
	v_lshlrev_b32_e32 v162, 16, v184
	v_and_b32_e32 v163, 0xffff0000, v184
	v_lshlrev_b32_e32 v184, 16, v185
	v_and_b32_e32 v185, 0xffff0000, v185
	v_lshlrev_b32_e32 v188, 16, v186
	v_and_b32_e32 v189, 0xffff0000, v186
	v_lshlrev_b32_e32 v186, 16, v187
	v_and_b32_e32 v187, 0xffff0000, v187
	v_pk_fma_f32 v[144:145], v[144:145], v[128:129], v[162:163]
	v_pk_fma_f32 v[146:147], v[146:147], v[130:131], v[184:185]
	v_pk_fma_f32 v[162:163], v[142:143], v[122:123], v[186:187]
	v_pk_fma_f32 v[184:185], v[140:141], v[120:121], v[188:189]
	v_pk_mul_f32 v[142:143], v[162:163], v[162:163]
	v_pk_mul_f32 v[140:141], v[184:185], v[184:185]
	v_pk_fma_f32 v[142:143], v[146:147], v[146:147], v[142:143]
	v_pk_fma_f32 v[140:141], v[144:145], v[144:145], v[140:141]
	v_lshl_add_u64 v[186:187], s[82:83], 0, v[224:225]
	v_add_f32_e32 v140, v140, v141
	v_add_f32_e32 v141, v142, v143
	v_add_f32_e32 v188, v140, v141
	v_cvt_pk_bf16_f32 v140, v144, v145
	v_cvt_pk_bf16_f32 v141, v146, v147
	v_cvt_pk_bf16_f32 v142, v184, v185
	v_cvt_pk_bf16_f32 v143, v162, v163
	v_lshl_add_u64 v[186:187], v[186:187], 0, v[210:211]
	s_nop 0
	global_store_dwordx4 v[186:187], v[140:143], off sc1

.LBB0_1179:
	s_or_b64 exec, exec, s[68:69]
	v_or_b32_e32 v140, 16, v156
	v_ashrrev_i32_e32 v141, 31, v140
	v_lshlrev_b64 v[144:145], 11, v[140:141]
	s_waitcnt lgkmcnt(0)
	v_lshl_add_u64 v[132:133], s[82:83], 0, v[144:145]
	v_lshl_add_u64 v[142:143], v[132:133], 0, v[210:211]
	global_load_dwordx4 v[136:139], v[142:143], off
	global_load_dwordx4 v[132:135], v[142:143], off offset:256
	v_lshlrev_b32_e32 v146, 16, v176
	v_and_b32_e32 v147, 0xffff0000, v176
	v_lshlrev_b32_e32 v162, 16, v177
	v_and_b32_e32 v163, 0xffff0000, v177
	v_lshlrev_b32_e32 v176, 16, v178
	v_and_b32_e32 v177, 0xffff0000, v178
	v_lshlrev_b32_e32 v178, 16, v179
	v_and_b32_e32 v179, 0xffff0000, v179
	v_pk_fma_f32 v[124:125], v[124:125], v[128:129], v[146:147]
	v_pk_fma_f32 v[126:127], v[126:127], v[130:131], v[162:163]
	v_pk_fma_f32 v[146:147], v[118:119], v[122:123], v[178:179]
	v_pk_fma_f32 v[162:163], v[116:117], v[120:121], v[176:177]
	v_pk_mul_f32 v[118:119], v[146:147], v[146:147]
	v_pk_mul_f32 v[116:117], v[162:163], v[162:163]
	v_pk_fma_f32 v[118:119], v[126:127], v[126:127], v[118:119]
	v_pk_fma_f32 v[116:117], v[124:125], v[124:125], v[116:117]
	v_lshl_add_u64 v[176:177], s[82:83], 0, v[218:219]
	v_add_f32_e32 v116, v116, v117
	v_add_f32_e32 v117, v118, v119
	v_add_f32_e32 v178, v116, v117
	v_cvt_pk_bf16_f32 v116, v124, v125
	v_cvt_pk_bf16_f32 v117, v126, v127
	v_cvt_pk_bf16_f32 v118, v162, v163
	v_cvt_pk_bf16_f32 v119, v146, v147
	v_lshl_add_u64 v[176:177], v[176:177], 0, v[210:211]
	s_nop 0
	global_store_dwordx4 v[176:177], v[116:119], off sc1

.LBB0_1181:
	s_or_b64 exec, exec, s[68:69]
	v_or_b32_e32 v116, 32, v156
	v_ashrrev_i32_e32 v117, 31, v116
	v_lshlrev_b64 v[124:125], 11, v[116:117]
	s_waitcnt lgkmcnt(0)
	v_lshl_add_u64 v[82:83], s[82:83], 0, v[124:125]
	v_lshl_add_u64 v[118:119], v[82:83], 0, v[210:211]
	global_load_dwordx4 v[86:89], v[118:119], off
	global_load_dwordx4 v[82:85], v[118:119], off offset:256
	v_lshlrev_b32_e32 v126, 16, v168
	v_and_b32_e32 v127, 0xffff0000, v168
	v_lshlrev_b32_e32 v146, 16, v169
	v_and_b32_e32 v147, 0xffff0000, v169
	v_lshlrev_b32_e32 v162, 16, v170
	v_and_b32_e32 v163, 0xffff0000, v170
	v_lshlrev_b32_e32 v168, 16, v171
	v_and_b32_e32 v169, 0xffff0000, v171
	v_pk_fma_f32 v[78:79], v[78:79], v[128:129], v[126:127]
	v_pk_fma_f32 v[80:81], v[80:81], v[130:131], v[146:147]
	v_pk_fma_f32 v[126:127], v[76:77], v[122:123], v[168:169]
	v_pk_fma_f32 v[146:147], v[74:75], v[120:121], v[162:163]
	v_pk_mul_f32 v[76:77], v[126:127], v[126:127]
	v_pk_mul_f32 v[74:75], v[146:147], v[146:147]
	v_pk_fma_f32 v[76:77], v[80:81], v[80:81], v[76:77]
	v_pk_fma_f32 v[74:75], v[78:79], v[78:79], v[74:75]
	v_lshl_add_u64 v[162:163], s[82:83], 0, v[214:215]
	v_add_f32_e32 v74, v74, v75
	v_add_f32_e32 v75, v76, v77
	v_add_f32_e32 v168, v74, v75
	v_cvt_pk_bf16_f32 v74, v78, v79
	v_cvt_pk_bf16_f32 v75, v80, v81
	v_cvt_pk_bf16_f32 v76, v146, v147
	v_cvt_pk_bf16_f32 v77, v126, v127
	v_lshl_add_u64 v[162:163], v[162:163], 0, v[210:211]
	s_nop 0
	global_store_dwordx4 v[162:163], v[74:77], off sc1
